# peel-first-K-iter-drop-acc-clears
# speedup vs baseline: 1.0061x; 1.0061x over previous
;     ...
;         const bool has_next = S.next(ui + 1, nxt);
;         const unsigned nA = has_next ? (unsigned)nxt.pm * tstepA : cA, nB = has_next ? (unsigned)nxt.pn * tstepB : cB;
.LBB0_187:
	s_lshl_b32 s46, s45, 19
	s_and_b64 s[0:1], s[4:5], exec
	s_cselect_b32 s0, s46, s3
	s_lshl_b32 s47, s44, 19
	s_and_b64 s[8:9], s[4:5], exec
	v_mov_b32_e32 v0, 0
	s_cselect_b32 s1, s47, s2
	v_add_u32_e32 v134, s3, v145
	v_add_u32_e32 v135, s3, v146
	s_addk_i32 s2, 0x100
	s_addk_i32 s3, 0x100
	s_mov_b32 s8, -2
	ds_read_b128 v[152:155], v147
	ds_read_b128 v[156:159], v147 offset:1024
	ds_read_b128 v[160:163], v147 offset:2048
	ds_read_b128 v[164:167], v147 offset:3072
	ds_read_b128 v[168:171], v149
	ds_read_b128 v[172:175], v149 offset:1024
	ds_read_b128 v[176:179], v149 offset:2048
	ds_read_b128 v[180:183], v149 offset:3072
	s_cmp_eq_u32 s8, 12
	s_cselect_b32 s49, s0, s3
	s_cselect_b32 s48, s1, s2
	s_or_b32 s9, s49, 0x80
	v_mov_b32_e32 v136, v135
	ds_read_b128 v[188:191], v150
	ds_read_b128 v[192:195], v150 offset:1024
	ds_read_b128 v[196:199], v150 offset:2048
	ds_read_b128 v[200:203], v150 offset:3072
	ds_read_b128 v[204:207], v150 offset:4096
	ds_read_b128 v[208:211], v150 offset:5120
	ds_read_b128 v[212:215], v150 offset:6144
	ds_read_b128 v[216:219], v150 offset:7168
	s_add_i32 m0, s25, 0xc000
	s_nop 0
	global_load_lds_dwordx4 v136, s[10:11]
	v_mov_b32_e32 v136, v134
	s_add_i32 m0, s25, 0xe000
	s_nop 0
	global_load_lds_dwordx4 v136, s[10:11]
	s_waitcnt vmcnt(8)
	s_waitcnt lgkmcnt(0)
	s_barrier
	s_waitcnt lgkmcnt(0)
	v_mfma_f32_16x16x32_bf16 v[124:127], v[152:155], v[188:191], 0
	v_mfma_f32_16x16x32_bf16 v[120:123], v[160:163], v[188:191], 0
	v_mfma_f32_16x16x32_bf16 v[108:111], v[152:155], v[196:199], 0
	v_mfma_f32_16x16x32_bf16 v[104:107], v[160:163], v[196:199], 0
	v_mfma_f32_16x16x32_bf16 v[92:95], v[152:155], v[204:207], 0
	v_mfma_f32_16x16x32_bf16 v[88:91], v[160:163], v[204:207], 0
	v_mfma_f32_16x16x32_bf16 v[76:79], v[152:155], v[212:215], 0
	v_mfma_f32_16x16x32_bf16 v[72:75], v[160:163], v[212:215], 0
	v_mfma_f32_16x16x32_bf16 v[124:127], v[156:159], v[192:195], v[124:127]
	v_mfma_f32_16x16x32_bf16 v[120:123], v[164:167], v[192:195], v[120:123]
	v_mfma_f32_16x16x32_bf16 v[108:111], v[156:159], v[200:203], v[108:111]
	v_mfma_f32_16x16x32_bf16 v[104:107], v[164:167], v[200:203], v[104:107]
	v_mfma_f32_16x16x32_bf16 v[92:95], v[156:159], v[208:211], v[92:95]
	v_mfma_f32_16x16x32_bf16 v[88:91], v[164:167], v[208:211], v[88:91]
	v_mfma_f32_16x16x32_bf16 v[76:79], v[156:159], v[216:219], v[76:79]
	v_mfma_f32_16x16x32_bf16 v[72:75], v[164:167], v[216:219], v[72:75]
	v_mfma_f32_16x16x32_bf16 v[116:119], v[168:171], v[188:191], 0
	v_mfma_f32_16x16x32_bf16 v[112:115], v[176:179], v[188:191], 0
	v_mfma_f32_16x16x32_bf16 v[100:103], v[168:171], v[196:199], 0
	v_mfma_f32_16x16x32_bf16 v[96:99], v[176:179], v[196:199], 0
	v_mfma_f32_16x16x32_bf16 v[84:87], v[168:171], v[204:207], 0
	v_mfma_f32_16x16x32_bf16 v[80:83], v[176:179], v[204:207], 0
	v_mfma_f32_16x16x32_bf16 v[68:71], v[168:171], v[212:215], 0
	v_mfma_f32_16x16x32_bf16 v[64:67], v[176:179], v[212:215], 0
	v_mfma_f32_16x16x32_bf16 v[116:119], v[172:175], v[192:195], v[116:119]
	v_mfma_f32_16x16x32_bf16 v[112:115], v[180:183], v[192:195], v[112:115]
	v_mfma_f32_16x16x32_bf16 v[100:103], v[172:175], v[200:203], v[100:103]
	v_mfma_f32_16x16x32_bf16 v[96:99], v[180:183], v[200:203], v[96:99]
	v_mfma_f32_16x16x32_bf16 v[84:87], v[172:175], v[208:211], v[84:87]
	v_mfma_f32_16x16x32_bf16 v[80:83], v[180:183], v[208:211], v[80:83]
	v_mfma_f32_16x16x32_bf16 v[68:71], v[172:175], v[216:219], v[68:71]
	v_mfma_f32_16x16x32_bf16 v[64:67], v[180:183], v[216:219], v[64:67]
	s_barrier
	v_add_u32_e32 v136, s48, v139
	s_add_i32 s50, s41, s24
	ds_read_b128 v[188:191], v150 offset:16384
	ds_read_b128 v[192:195], v150 offset:17408
	ds_read_b128 v[196:199], v150 offset:18432
	ds_read_b128 v[200:203], v150 offset:19456
	ds_read_b128 v[204:207], v150 offset:20480
	ds_read_b128 v[208:211], v150 offset:21504
	ds_read_b128 v[212:215], v150 offset:22528
	ds_read_b128 v[216:219], v150 offset:23552
	s_mov_b32 m0, s50
	s_add_i32 s51, s42, s24
	global_load_lds_dwordx4 v136, s[12:13]
	v_add_u32_e32 v136, s48, v141
	s_add_i32 m0, s50, 0x2000
	s_add_i32 s50, s48, 0x40000
	global_load_lds_dwordx4 v136, s[12:13]
	v_add_u32_e32 v136, s50, v139
	s_mov_b32 m0, s51
	s_nop 0
	global_load_lds_dwordx4 v136, s[12:13]
	v_add_u32_e32 v136, s50, v141
	s_add_i32 m0, s51, 0x2000
	s_nop 0
	global_load_lds_dwordx4 v136, s[12:13]
	v_add_u32_e32 v136, s49, v138
	s_mov_b32 m0, s25
	s_nop 0
	global_load_lds_dwordx4 v136, s[10:11]
	v_add_u32_e32 v136, s49, v140
	s_mov_b32 m0, s26
	s_nop 0
	global_load_lds_dwordx4 v136, s[10:11]
	s_waitcnt vmcnt(8)
	s_waitcnt lgkmcnt(0)
	s_barrier
	s_waitcnt lgkmcnt(0)
	v_mfma_f32_16x16x32_bf16 v[60:63], v[152:155], v[188:191], 0
	v_mfma_f32_16x16x32_bf16 v[56:59], v[160:163], v[188:191], 0
	v_mfma_f32_16x16x32_bf16 v[44:47], v[152:155], v[196:199], 0
	v_mfma_f32_16x16x32_bf16 v[40:43], v[160:163], v[196:199], 0
	v_mfma_f32_16x16x32_bf16 v[28:31], v[152:155], v[204:207], 0
	v_mfma_f32_16x16x32_bf16 v[24:27], v[160:163], v[204:207], 0
	v_mfma_f32_16x16x32_bf16 v[12:15], v[152:155], v[212:215], 0
	v_mfma_f32_16x16x32_bf16 v[8:11], v[160:163], v[212:215], 0
	v_mfma_f32_16x16x32_bf16 v[60:63], v[156:159], v[192:195], v[60:63]
	v_mfma_f32_16x16x32_bf16 v[56:59], v[164:167], v[192:195], v[56:59]
	v_mfma_f32_16x16x32_bf16 v[44:47], v[156:159], v[200:203], v[44:47]
	v_mfma_f32_16x16x32_bf16 v[40:43], v[164:167], v[200:203], v[40:43]
	v_mfma_f32_16x16x32_bf16 v[28:31], v[156:159], v[208:211], v[28:31]
	v_mfma_f32_16x16x32_bf16 v[24:27], v[164:167], v[208:211], v[24:27]
	v_mfma_f32_16x16x32_bf16 v[12:15], v[156:159], v[216:219], v[12:15]
	v_mfma_f32_16x16x32_bf16 v[8:11], v[164:167], v[216:219], v[8:11]
	v_mfma_f32_16x16x32_bf16 v[52:55], v[168:171], v[188:191], 0
	v_mfma_f32_16x16x32_bf16 v[48:51], v[176:179], v[188:191], 0
	v_mfma_f32_16x16x32_bf16 v[36:39], v[168:171], v[196:199], 0
	v_mfma_f32_16x16x32_bf16 v[32:35], v[176:179], v[196:199], 0
	v_mfma_f32_16x16x32_bf16 v[20:23], v[168:171], v[204:207], 0
	v_mfma_f32_16x16x32_bf16 v[16:19], v[176:179], v[204:207], 0
	v_mfma_f32_16x16x32_bf16 v[4:7], v[168:171], v[212:215], 0
	v_mfma_f32_16x16x32_bf16 v[0:3], v[176:179], v[212:215], 0
	v_mfma_f32_16x16x32_bf16 v[52:55], v[172:175], v[192:195], v[52:55]
	v_mfma_f32_16x16x32_bf16 v[48:51], v[180:183], v[192:195], v[48:51]
	v_mfma_f32_16x16x32_bf16 v[36:39], v[172:175], v[200:203], v[36:39]
	v_mfma_f32_16x16x32_bf16 v[32:35], v[180:183], v[200:203], v[32:35]
	v_mfma_f32_16x16x32_bf16 v[20:23], v[172:175], v[208:211], v[20:23]
	v_mfma_f32_16x16x32_bf16 v[16:19], v[180:183], v[208:211], v[16:19]
	v_mfma_f32_16x16x32_bf16 v[4:7], v[172:175], v[216:219], v[4:7]
	v_mfma_f32_16x16x32_bf16 v[0:3], v[180:183], v[216:219], v[0:3]
	s_barrier
;     ...
;         if constexpr (Epi::MIDHOOK) {
;             for (int t = 0; t < 4; t += 2) PG8_ITER(t);
;             E.mid(acc, cur, wr, wc, fr, fq);
;             for (int t = 4; t < nt; t += 2) PG8_ITER(t);
;         } else {
;             for (int t = 0; t < nt; t += 2) PG8_ITER(t);
	s_add_i32 s50, 0, 0x18000
	v_add_u32_e32 v136, s50, v143
	s_add_i32 s51, 0, 0x1c000
	ds_read_b128 v[152:155], v136
	ds_read_b128 v[156:159], v136 offset:1024
	ds_read_b128 v[160:163], v136 offset:2048
	ds_read_b128 v[164:167], v136 offset:3072
	v_add_u32_e32 v136, s51, v143
	ds_read_b128 v[168:171], v136
	ds_read_b128 v[172:175], v136 offset:1024
	ds_read_b128 v[176:179], v136 offset:2048
	ds_read_b128 v[180:183], v136 offset:3072
	s_add_i32 s49, s49, 0x40000
	v_add_u32_e32 v136, s49, v138
	s_mov_b32 m0, s27
	ds_read_b128 v[188:191], v150 offset:32768
	ds_read_b128 v[192:195], v150 offset:33792
	ds_read_b128 v[196:199], v150 offset:34816
	ds_read_b128 v[200:203], v150 offset:35840
	ds_read_b128 v[204:207], v150 offset:36864
	ds_read_b128 v[208:211], v150 offset:37888
	ds_read_b128 v[212:215], v150 offset:38912
	ds_read_b128 v[216:219], v150 offset:39936
	s_nop 0
	global_load_lds_dwordx4 v136, s[10:11]
	v_add_u32_e32 v136, s49, v140
	s_mov_b32 m0, s28
	s_nop 0
	global_load_lds_dwordx4 v136, s[10:11]
	s_waitcnt vmcnt(8)
	s_waitcnt lgkmcnt(0)
	s_barrier
	s_waitcnt lgkmcnt(0)
	v_mfma_f32_16x16x32_bf16 v[124:127], v[152:155], v[188:191], v[124:127]
	v_mfma_f32_16x16x32_bf16 v[120:123], v[160:163], v[188:191], v[120:123]
	v_mfma_f32_16x16x32_bf16 v[108:111], v[152:155], v[196:199], v[108:111]
	v_mfma_f32_16x16x32_bf16 v[104:107], v[160:163], v[196:199], v[104:107]
	v_mfma_f32_16x16x32_bf16 v[92:95], v[152:155], v[204:207], v[92:95]
	v_mfma_f32_16x16x32_bf16 v[88:91], v[160:163], v[204:207], v[88:91]
	v_mfma_f32_16x16x32_bf16 v[76:79], v[152:155], v[212:215], v[76:79]
	v_mfma_f32_16x16x32_bf16 v[72:75], v[160:163], v[212:215], v[72:75]
	v_mfma_f32_16x16x32_bf16 v[124:127], v[156:159], v[192:195], v[124:127]
	v_mfma_f32_16x16x32_bf16 v[120:123], v[164:167], v[192:195], v[120:123]
	v_mfma_f32_16x16x32_bf16 v[108:111], v[156:159], v[200:203], v[108:111]
	v_mfma_f32_16x16x32_bf16 v[104:107], v[164:167], v[200:203], v[104:107]
	v_mfma_f32_16x16x32_bf16 v[92:95], v[156:159], v[208:211], v[92:95]
	v_mfma_f32_16x16x32_bf16 v[88:91], v[164:167], v[208:211], v[88:91]
	v_mfma_f32_16x16x32_bf16 v[76:79], v[156:159], v[216:219], v[76:79]
	v_mfma_f32_16x16x32_bf16 v[72:75], v[164:167], v[216:219], v[72:75]
	v_mfma_f32_16x16x32_bf16 v[116:119], v[168:171], v[188:191], v[116:119]
	v_mfma_f32_16x16x32_bf16 v[112:115], v[176:179], v[188:191], v[112:115]
	v_mfma_f32_16x16x32_bf16 v[100:103], v[168:171], v[196:199], v[100:103]
	v_mfma_f32_16x16x32_bf16 v[96:99], v[176:179], v[196:199], v[96:99]
	v_mfma_f32_16x16x32_bf16 v[84:87], v[168:171], v[204:207], v[84:87]
	v_mfma_f32_16x16x32_bf16 v[80:83], v[176:179], v[204:207], v[80:83]
	v_mfma_f32_16x16x32_bf16 v[68:71], v[168:171], v[212:215], v[68:71]
	v_mfma_f32_16x16x32_bf16 v[64:67], v[176:179], v[212:215], v[64:67]
	v_mfma_f32_16x16x32_bf16 v[116:119], v[172:175], v[192:195], v[116:119]
	v_mfma_f32_16x16x32_bf16 v[112:115], v[180:183], v[192:195], v[112:115]
	v_mfma_f32_16x16x32_bf16 v[100:103], v[172:175], v[200:203], v[100:103]
	v_mfma_f32_16x16x32_bf16 v[96:99], v[180:183], v[200:203], v[96:99]
	v_mfma_f32_16x16x32_bf16 v[84:87], v[172:175], v[208:211], v[84:87]
	v_mfma_f32_16x16x32_bf16 v[80:83], v[180:183], v[208:211], v[80:83]
	v_mfma_f32_16x16x32_bf16 v[68:71], v[172:175], v[216:219], v[68:71]
	v_mfma_f32_16x16x32_bf16 v[64:67], v[180:183], v[216:219], v[64:67]
	s_barrier
	s_or_b32 s49, s48, 0x80
	v_add_u32_e32 v136, s49, v139
	s_add_i32 s50, s50, s24
	ds_read_b128 v[188:191], v150 offset:49152
	ds_read_b128 v[192:195], v150 offset:50176
	ds_read_b128 v[196:199], v150 offset:51200
	ds_read_b128 v[200:203], v150 offset:52224
	ds_read_b128 v[204:207], v150 offset:53248
	ds_read_b128 v[208:211], v150 offset:54272
	ds_read_b128 v[212:215], v150 offset:55296
	ds_read_b128 v[216:219], v150 offset:56320
	s_mov_b32 m0, s50
	s_add_i32 s48, s48, 0x40080
	global_load_lds_dwordx4 v136, s[12:13]
	v_add_u32_e32 v136, s49, v141
	s_add_i32 m0, s50, 0x2000
	s_add_i32 s49, s51, s24
	global_load_lds_dwordx4 v136, s[12:13]
	v_add_u32_e32 v136, s48, v139
	s_mov_b32 m0, s49
	s_nop 0
	global_load_lds_dwordx4 v136, s[12:13]
	v_add_u32_e32 v136, s48, v141
	s_add_i32 m0, s49, 0x2000
	s_nop 0
	global_load_lds_dwordx4 v136, s[12:13]
	v_add_u32_e32 v136, s9, v138
	s_mov_b32 m0, s30
	s_nop 0
	global_load_lds_dwordx4 v136, s[10:11]
	v_add_u32_e32 v136, s9, v140
	s_mov_b32 m0, s31
	s_nop 0
	global_load_lds_dwordx4 v136, s[10:11]
	s_waitcnt vmcnt(8)
	s_waitcnt lgkmcnt(0)
	s_barrier
	s_waitcnt lgkmcnt(0)
	v_mfma_f32_16x16x32_bf16 v[60:63], v[152:155], v[188:191], v[60:63]
	v_mfma_f32_16x16x32_bf16 v[56:59], v[160:163], v[188:191], v[56:59]
	v_mfma_f32_16x16x32_bf16 v[44:47], v[152:155], v[196:199], v[44:47]
	v_mfma_f32_16x16x32_bf16 v[40:43], v[160:163], v[196:199], v[40:43]
	v_mfma_f32_16x16x32_bf16 v[28:31], v[152:155], v[204:207], v[28:31]
	v_mfma_f32_16x16x32_bf16 v[24:27], v[160:163], v[204:207], v[24:27]
	v_mfma_f32_16x16x32_bf16 v[12:15], v[152:155], v[212:215], v[12:15]
	v_mfma_f32_16x16x32_bf16 v[8:11], v[160:163], v[212:215], v[8:11]
	v_mfma_f32_16x16x32_bf16 v[60:63], v[156:159], v[192:195], v[60:63]
	v_mfma_f32_16x16x32_bf16 v[56:59], v[164:167], v[192:195], v[56:59]
	v_mfma_f32_16x16x32_bf16 v[44:47], v[156:159], v[200:203], v[44:47]
	v_mfma_f32_16x16x32_bf16 v[40:43], v[164:167], v[200:203], v[40:43]
	v_mfma_f32_16x16x32_bf16 v[28:31], v[156:159], v[208:211], v[28:31]
	v_mfma_f32_16x16x32_bf16 v[24:27], v[164:167], v[208:211], v[24:27]
	v_mfma_f32_16x16x32_bf16 v[12:15], v[156:159], v[216:219], v[12:15]
	v_mfma_f32_16x16x32_bf16 v[8:11], v[164:167], v[216:219], v[8:11]
	v_mfma_f32_16x16x32_bf16 v[52:55], v[168:171], v[188:191], v[52:55]
	v_mfma_f32_16x16x32_bf16 v[48:51], v[176:179], v[188:191], v[48:51]
	v_mfma_f32_16x16x32_bf16 v[36:39], v[168:171], v[196:199], v[36:39]
	v_mfma_f32_16x16x32_bf16 v[32:35], v[176:179], v[196:199], v[32:35]
	v_mfma_f32_16x16x32_bf16 v[20:23], v[168:171], v[204:207], v[20:23]
	v_mfma_f32_16x16x32_bf16 v[16:19], v[176:179], v[204:207], v[16:19]
	v_mfma_f32_16x16x32_bf16 v[4:7], v[168:171], v[212:215], v[4:7]
	v_mfma_f32_16x16x32_bf16 v[0:3], v[176:179], v[212:215], v[0:3]
	v_mfma_f32_16x16x32_bf16 v[52:55], v[172:175], v[192:195], v[52:55]
	v_mfma_f32_16x16x32_bf16 v[48:51], v[180:183], v[192:195], v[48:51]
	v_mfma_f32_16x16x32_bf16 v[36:39], v[172:175], v[200:203], v[36:39]
	v_mfma_f32_16x16x32_bf16 v[32:35], v[180:183], v[200:203], v[32:35]
	v_mfma_f32_16x16x32_bf16 v[20:23], v[172:175], v[208:211], v[20:23]
	v_mfma_f32_16x16x32_bf16 v[16:19], v[180:183], v[208:211], v[16:19]
	v_mfma_f32_16x16x32_bf16 v[4:7], v[172:175], v[216:219], v[4:7]
	v_mfma_f32_16x16x32_bf16 v[0:3], v[180:183], v[216:219], v[0:3]
	s_barrier
	s_add_i32 s8, s8, 2
	s_addk_i32 s2, 0x100
	s_addk_i32 s3, 0x100
	v_add_u32_e32 v134, 0x100, v134
	s_cmp_gt_u32 s8, 13
	v_add_u32_e32 v135, 0x100, v135
	s_cbranch_scc1 .Lpeel_done_188
.LBB0_188:
	ds_read_b128 v[152:155], v147
	ds_read_b128 v[156:159], v147 offset:1024
	ds_read_b128 v[160:163], v147 offset:2048
	ds_read_b128 v[164:167], v147 offset:3072
	ds_read_b128 v[168:171], v149
	ds_read_b128 v[172:175], v149 offset:1024
	ds_read_b128 v[176:179], v149 offset:2048
	ds_read_b128 v[180:183], v149 offset:3072
	s_cmp_eq_u32 s8, 12
	s_cselect_b32 s49, s0, s3
	s_cselect_b32 s48, s1, s2
	s_or_b32 s9, s49, 0x80
	v_mov_b32_e32 v136, v135
	ds_read_b128 v[188:191], v150
	ds_read_b128 v[192:195], v150 offset:1024
	ds_read_b128 v[196:199], v150 offset:2048
	ds_read_b128 v[200:203], v150 offset:3072
	ds_read_b128 v[204:207], v150 offset:4096
	ds_read_b128 v[208:211], v150 offset:5120
	ds_read_b128 v[212:215], v150 offset:6144
	ds_read_b128 v[216:219], v150 offset:7168
	s_add_i32 m0, s25, 0xc000
	s_nop 0
	global_load_lds_dwordx4 v136, s[10:11]
	v_mov_b32_e32 v136, v134
	s_add_i32 m0, s25, 0xe000
	s_nop 0
	global_load_lds_dwordx4 v136, s[10:11]
	s_waitcnt vmcnt(8)
	s_waitcnt lgkmcnt(0)
	s_barrier
	s_waitcnt lgkmcnt(0)
	v_mfma_f32_16x16x32_bf16 v[124:127], v[152:155], v[188:191], v[124:127]
	v_mfma_f32_16x16x32_bf16 v[120:123], v[160:163], v[188:191], v[120:123]
	v_mfma_f32_16x16x32_bf16 v[108:111], v[152:155], v[196:199], v[108:111]
	v_mfma_f32_16x16x32_bf16 v[104:107], v[160:163], v[196:199], v[104:107]
	v_mfma_f32_16x16x32_bf16 v[92:95], v[152:155], v[204:207], v[92:95]
	v_mfma_f32_16x16x32_bf16 v[88:91], v[160:163], v[204:207], v[88:91]
	v_mfma_f32_16x16x32_bf16 v[76:79], v[152:155], v[212:215], v[76:79]
	v_mfma_f32_16x16x32_bf16 v[72:75], v[160:163], v[212:215], v[72:75]
	v_mfma_f32_16x16x32_bf16 v[124:127], v[156:159], v[192:195], v[124:127]
	v_mfma_f32_16x16x32_bf16 v[120:123], v[164:167], v[192:195], v[120:123]
	v_mfma_f32_16x16x32_bf16 v[108:111], v[156:159], v[200:203], v[108:111]
	v_mfma_f32_16x16x32_bf16 v[104:107], v[164:167], v[200:203], v[104:107]
	v_mfma_f32_16x16x32_bf16 v[92:95], v[156:159], v[208:211], v[92:95]
	v_mfma_f32_16x16x32_bf16 v[88:91], v[164:167], v[208:211], v[88:91]
	v_mfma_f32_16x16x32_bf16 v[76:79], v[156:159], v[216:219], v[76:79]
	v_mfma_f32_16x16x32_bf16 v[72:75], v[164:167], v[216:219], v[72:75]
	v_mfma_f32_16x16x32_bf16 v[116:119], v[168:171], v[188:191], v[116:119]
	v_mfma_f32_16x16x32_bf16 v[112:115], v[176:179], v[188:191], v[112:115]
	v_mfma_f32_16x16x32_bf16 v[100:103], v[168:171], v[196:199], v[100:103]
	v_mfma_f32_16x16x32_bf16 v[96:99], v[176:179], v[196:199], v[96:99]
	v_mfma_f32_16x16x32_bf16 v[84:87], v[168:171], v[204:207], v[84:87]
	v_mfma_f32_16x16x32_bf16 v[80:83], v[176:179], v[204:207], v[80:83]
	v_mfma_f32_16x16x32_bf16 v[68:71], v[168:171], v[212:215], v[68:71]
	v_mfma_f32_16x16x32_bf16 v[64:67], v[176:179], v[212:215], v[64:67]
	v_mfma_f32_16x16x32_bf16 v[116:119], v[172:175], v[192:195], v[116:119]
	v_mfma_f32_16x16x32_bf16 v[112:115], v[180:183], v[192:195], v[112:115]
	v_mfma_f32_16x16x32_bf16 v[100:103], v[172:175], v[200:203], v[100:103]
	v_mfma_f32_16x16x32_bf16 v[96:99], v[180:183], v[200:203], v[96:99]
	v_mfma_f32_16x16x32_bf16 v[84:87], v[172:175], v[208:211], v[84:87]
	v_mfma_f32_16x16x32_bf16 v[80:83], v[180:183], v[208:211], v[80:83]
	v_mfma_f32_16x16x32_bf16 v[68:71], v[172:175], v[216:219], v[68:71]
	v_mfma_f32_16x16x32_bf16 v[64:67], v[180:183], v[216:219], v[64:67]
	s_barrier
	v_add_u32_e32 v136, s48, v139
	s_add_i32 s50, s41, s24
	ds_read_b128 v[188:191], v150 offset:16384
	ds_read_b128 v[192:195], v150 offset:17408
	ds_read_b128 v[196:199], v150 offset:18432
	ds_read_b128 v[200:203], v150 offset:19456
	ds_read_b128 v[204:207], v150 offset:20480
	ds_read_b128 v[208:211], v150 offset:21504
	ds_read_b128 v[212:215], v150 offset:22528
	ds_read_b128 v[216:219], v150 offset:23552
	s_mov_b32 m0, s50
	s_add_i32 s51, s42, s24
	global_load_lds_dwordx4 v136, s[12:13]
	v_add_u32_e32 v136, s48, v141
	s_add_i32 m0, s50, 0x2000
	s_add_i32 s50, s48, 0x40000
	global_load_lds_dwordx4 v136, s[12:13]
	v_add_u32_e32 v136, s50, v139
	s_mov_b32 m0, s51
	s_nop 0
	global_load_lds_dwordx4 v136, s[12:13]
	v_add_u32_e32 v136, s50, v141
	s_add_i32 m0, s51, 0x2000
	s_nop 0
	global_load_lds_dwordx4 v136, s[12:13]
	v_add_u32_e32 v136, s49, v138
	s_mov_b32 m0, s25
	s_nop 0
	global_load_lds_dwordx4 v136, s[10:11]
	v_add_u32_e32 v136, s49, v140
	s_mov_b32 m0, s26
	s_nop 0
	global_load_lds_dwordx4 v136, s[10:11]
	s_waitcnt vmcnt(8)
	s_waitcnt lgkmcnt(0)
	s_barrier
	s_waitcnt lgkmcnt(0)
	v_mfma_f32_16x16x32_bf16 v[60:63], v[152:155], v[188:191], v[60:63]
	v_mfma_f32_16x16x32_bf16 v[56:59], v[160:163], v[188:191], v[56:59]
	v_mfma_f32_16x16x32_bf16 v[44:47], v[152:155], v[196:199], v[44:47]
	v_mfma_f32_16x16x32_bf16 v[40:43], v[160:163], v[196:199], v[40:43]
	v_mfma_f32_16x16x32_bf16 v[28:31], v[152:155], v[204:207], v[28:31]
	v_mfma_f32_16x16x32_bf16 v[24:27], v[160:163], v[204:207], v[24:27]
	v_mfma_f32_16x16x32_bf16 v[12:15], v[152:155], v[212:215], v[12:15]
	v_mfma_f32_16x16x32_bf16 v[8:11], v[160:163], v[212:215], v[8:11]
	v_mfma_f32_16x16x32_bf16 v[60:63], v[156:159], v[192:195], v[60:63]
	v_mfma_f32_16x16x32_bf16 v[56:59], v[164:167], v[192:195], v[56:59]
	v_mfma_f32_16x16x32_bf16 v[44:47], v[156:159], v[200:203], v[44:47]
	v_mfma_f32_16x16x32_bf16 v[40:43], v[164:167], v[200:203], v[40:43]
	v_mfma_f32_16x16x32_bf16 v[28:31], v[156:159], v[208:211], v[28:31]
	v_mfma_f32_16x16x32_bf16 v[24:27], v[164:167], v[208:211], v[24:27]
	v_mfma_f32_16x16x32_bf16 v[12:15], v[156:159], v[216:219], v[12:15]
	v_mfma_f32_16x16x32_bf16 v[8:11], v[164:167], v[216:219], v[8:11]
	v_mfma_f32_16x16x32_bf16 v[52:55], v[168:171], v[188:191], v[52:55]
	v_mfma_f32_16x16x32_bf16 v[48:51], v[176:179], v[188:191], v[48:51]
	v_mfma_f32_16x16x32_bf16 v[36:39], v[168:171], v[196:199], v[36:39]
	v_mfma_f32_16x16x32_bf16 v[32:35], v[176:179], v[196:199], v[32:35]
	v_mfma_f32_16x16x32_bf16 v[20:23], v[168:171], v[204:207], v[20:23]
	v_mfma_f32_16x16x32_bf16 v[16:19], v[176:179], v[204:207], v[16:19]
	v_mfma_f32_16x16x32_bf16 v[4:7], v[168:171], v[212:215], v[4:7]
	v_mfma_f32_16x16x32_bf16 v[0:3], v[176:179], v[212:215], v[0:3]
	v_mfma_f32_16x16x32_bf16 v[52:55], v[172:175], v[192:195], v[52:55]
	v_mfma_f32_16x16x32_bf16 v[48:51], v[180:183], v[192:195], v[48:51]
	v_mfma_f32_16x16x32_bf16 v[36:39], v[172:175], v[200:203], v[36:39]
	v_mfma_f32_16x16x32_bf16 v[32:35], v[180:183], v[200:203], v[32:35]
	v_mfma_f32_16x16x32_bf16 v[20:23], v[172:175], v[208:211], v[20:23]
	v_mfma_f32_16x16x32_bf16 v[16:19], v[180:183], v[208:211], v[16:19]
	v_mfma_f32_16x16x32_bf16 v[4:7], v[172:175], v[216:219], v[4:7]
	v_mfma_f32_16x16x32_bf16 v[0:3], v[180:183], v[216:219], v[0:3]
	s_barrier
; #define PG8_BAR __builtin_amdgcn_s_barrier()
;     ...
;         if constexpr (Epi::MIDHOOK) {
;             for (int t = 0; t < 4; t += 2) PG8_ITER(t);
;             E.mid(acc, cur, wr, wc, fr, fq);
;             for (int t = 4; t < nt; t += 2) PG8_ITER(t);
;         } else {
;             for (int t = 0; t < nt; t += 2) PG8_ITER(t);
;         }
;     ...
;         if constexpr (ALIGN_EPI) { if (wr == 0) PG8_BAR; }
	s_add_i32 s50, 0, 0x18000
	v_add_u32_e32 v136, s50, v143
	s_add_i32 s51, 0, 0x1c000
	ds_read_b128 v[152:155], v136
	ds_read_b128 v[156:159], v136 offset:1024
	ds_read_b128 v[160:163], v136 offset:2048
	ds_read_b128 v[164:167], v136 offset:3072
	v_add_u32_e32 v136, s51, v143
	ds_read_b128 v[168:171], v136
	ds_read_b128 v[172:175], v136 offset:1024
	ds_read_b128 v[176:179], v136 offset:2048
	ds_read_b128 v[180:183], v136 offset:3072
	s_add_i32 s49, s49, 0x40000
	v_add_u32_e32 v136, s49, v138
	s_mov_b32 m0, s27
	ds_read_b128 v[188:191], v150 offset:32768
	ds_read_b128 v[192:195], v150 offset:33792
	ds_read_b128 v[196:199], v150 offset:34816
	ds_read_b128 v[200:203], v150 offset:35840
	ds_read_b128 v[204:207], v150 offset:36864
	ds_read_b128 v[208:211], v150 offset:37888
	ds_read_b128 v[212:215], v150 offset:38912
	ds_read_b128 v[216:219], v150 offset:39936
	s_nop 0
	global_load_lds_dwordx4 v136, s[10:11]
	v_add_u32_e32 v136, s49, v140
	s_mov_b32 m0, s28
	s_nop 0
	global_load_lds_dwordx4 v136, s[10:11]
	s_waitcnt vmcnt(8)
	s_waitcnt lgkmcnt(0)
	s_barrier
	s_waitcnt lgkmcnt(0)
	v_mfma_f32_16x16x32_bf16 v[124:127], v[152:155], v[188:191], v[124:127]
	v_mfma_f32_16x16x32_bf16 v[120:123], v[160:163], v[188:191], v[120:123]
	v_mfma_f32_16x16x32_bf16 v[108:111], v[152:155], v[196:199], v[108:111]
	v_mfma_f32_16x16x32_bf16 v[104:107], v[160:163], v[196:199], v[104:107]
	v_mfma_f32_16x16x32_bf16 v[92:95], v[152:155], v[204:207], v[92:95]
	v_mfma_f32_16x16x32_bf16 v[88:91], v[160:163], v[204:207], v[88:91]
	v_mfma_f32_16x16x32_bf16 v[76:79], v[152:155], v[212:215], v[76:79]
	v_mfma_f32_16x16x32_bf16 v[72:75], v[160:163], v[212:215], v[72:75]
	v_mfma_f32_16x16x32_bf16 v[124:127], v[156:159], v[192:195], v[124:127]
	v_mfma_f32_16x16x32_bf16 v[120:123], v[164:167], v[192:195], v[120:123]
	v_mfma_f32_16x16x32_bf16 v[108:111], v[156:159], v[200:203], v[108:111]
	v_mfma_f32_16x16x32_bf16 v[104:107], v[164:167], v[200:203], v[104:107]
	v_mfma_f32_16x16x32_bf16 v[92:95], v[156:159], v[208:211], v[92:95]
	v_mfma_f32_16x16x32_bf16 v[88:91], v[164:167], v[208:211], v[88:91]
	v_mfma_f32_16x16x32_bf16 v[76:79], v[156:159], v[216:219], v[76:79]
	v_mfma_f32_16x16x32_bf16 v[72:75], v[164:167], v[216:219], v[72:75]
	v_mfma_f32_16x16x32_bf16 v[116:119], v[168:171], v[188:191], v[116:119]
	v_mfma_f32_16x16x32_bf16 v[112:115], v[176:179], v[188:191], v[112:115]
	v_mfma_f32_16x16x32_bf16 v[100:103], v[168:171], v[196:199], v[100:103]
	v_mfma_f32_16x16x32_bf16 v[96:99], v[176:179], v[196:199], v[96:99]
	v_mfma_f32_16x16x32_bf16 v[84:87], v[168:171], v[204:207], v[84:87]
	v_mfma_f32_16x16x32_bf16 v[80:83], v[176:179], v[204:207], v[80:83]
	v_mfma_f32_16x16x32_bf16 v[68:71], v[168:171], v[212:215], v[68:71]
	v_mfma_f32_16x16x32_bf16 v[64:67], v[176:179], v[212:215], v[64:67]
	v_mfma_f32_16x16x32_bf16 v[116:119], v[172:175], v[192:195], v[116:119]
	v_mfma_f32_16x16x32_bf16 v[112:115], v[180:183], v[192:195], v[112:115]
	v_mfma_f32_16x16x32_bf16 v[100:103], v[172:175], v[200:203], v[100:103]
	v_mfma_f32_16x16x32_bf16 v[96:99], v[180:183], v[200:203], v[96:99]
	v_mfma_f32_16x16x32_bf16 v[84:87], v[172:175], v[208:211], v[84:87]
	v_mfma_f32_16x16x32_bf16 v[80:83], v[180:183], v[208:211], v[80:83]
	v_mfma_f32_16x16x32_bf16 v[68:71], v[172:175], v[216:219], v[68:71]
	v_mfma_f32_16x16x32_bf16 v[64:67], v[180:183], v[216:219], v[64:67]
	s_barrier
	s_or_b32 s49, s48, 0x80
	v_add_u32_e32 v136, s49, v139
	s_add_i32 s50, s50, s24
	ds_read_b128 v[188:191], v150 offset:49152
	ds_read_b128 v[192:195], v150 offset:50176
	ds_read_b128 v[196:199], v150 offset:51200
	ds_read_b128 v[200:203], v150 offset:52224
	ds_read_b128 v[204:207], v150 offset:53248
	ds_read_b128 v[208:211], v150 offset:54272
	ds_read_b128 v[212:215], v150 offset:55296
	ds_read_b128 v[216:219], v150 offset:56320
	s_mov_b32 m0, s50
	s_add_i32 s48, s48, 0x40080
	global_load_lds_dwordx4 v136, s[12:13]
	v_add_u32_e32 v136, s49, v141
	s_add_i32 m0, s50, 0x2000
	s_add_i32 s49, s51, s24
	global_load_lds_dwordx4 v136, s[12:13]
	v_add_u32_e32 v136, s48, v139
	s_mov_b32 m0, s49
	s_nop 0
	global_load_lds_dwordx4 v136, s[12:13]
	v_add_u32_e32 v136, s48, v141
	s_add_i32 m0, s49, 0x2000
	s_nop 0
	global_load_lds_dwordx4 v136, s[12:13]
	v_add_u32_e32 v136, s9, v138
	s_mov_b32 m0, s30
	s_nop 0
	global_load_lds_dwordx4 v136, s[10:11]
	v_add_u32_e32 v136, s9, v140
	s_mov_b32 m0, s31
	s_nop 0
	global_load_lds_dwordx4 v136, s[10:11]
	s_waitcnt vmcnt(8)
	s_waitcnt lgkmcnt(0)
	s_barrier
	s_waitcnt lgkmcnt(0)
	v_mfma_f32_16x16x32_bf16 v[60:63], v[152:155], v[188:191], v[60:63]
	v_mfma_f32_16x16x32_bf16 v[56:59], v[160:163], v[188:191], v[56:59]
	v_mfma_f32_16x16x32_bf16 v[44:47], v[152:155], v[196:199], v[44:47]
	v_mfma_f32_16x16x32_bf16 v[40:43], v[160:163], v[196:199], v[40:43]
	v_mfma_f32_16x16x32_bf16 v[28:31], v[152:155], v[204:207], v[28:31]
	v_mfma_f32_16x16x32_bf16 v[24:27], v[160:163], v[204:207], v[24:27]
	v_mfma_f32_16x16x32_bf16 v[12:15], v[152:155], v[212:215], v[12:15]
	v_mfma_f32_16x16x32_bf16 v[8:11], v[160:163], v[212:215], v[8:11]
	v_mfma_f32_16x16x32_bf16 v[60:63], v[156:159], v[192:195], v[60:63]
	v_mfma_f32_16x16x32_bf16 v[56:59], v[164:167], v[192:195], v[56:59]
	v_mfma_f32_16x16x32_bf16 v[44:47], v[156:159], v[200:203], v[44:47]
	v_mfma_f32_16x16x32_bf16 v[40:43], v[164:167], v[200:203], v[40:43]
	v_mfma_f32_16x16x32_bf16 v[28:31], v[156:159], v[208:211], v[28:31]
	v_mfma_f32_16x16x32_bf16 v[24:27], v[164:167], v[208:211], v[24:27]
	v_mfma_f32_16x16x32_bf16 v[12:15], v[156:159], v[216:219], v[12:15]
	v_mfma_f32_16x16x32_bf16 v[8:11], v[164:167], v[216:219], v[8:11]
	v_mfma_f32_16x16x32_bf16 v[52:55], v[168:171], v[188:191], v[52:55]
	v_mfma_f32_16x16x32_bf16 v[48:51], v[176:179], v[188:191], v[48:51]
	v_mfma_f32_16x16x32_bf16 v[36:39], v[168:171], v[196:199], v[36:39]
	v_mfma_f32_16x16x32_bf16 v[32:35], v[176:179], v[196:199], v[32:35]
	v_mfma_f32_16x16x32_bf16 v[20:23], v[168:171], v[204:207], v[20:23]
	v_mfma_f32_16x16x32_bf16 v[16:19], v[176:179], v[204:207], v[16:19]
	v_mfma_f32_16x16x32_bf16 v[4:7], v[168:171], v[212:215], v[4:7]
	v_mfma_f32_16x16x32_bf16 v[0:3], v[176:179], v[212:215], v[0:3]
	v_mfma_f32_16x16x32_bf16 v[52:55], v[172:175], v[192:195], v[52:55]
	v_mfma_f32_16x16x32_bf16 v[48:51], v[180:183], v[192:195], v[48:51]
	v_mfma_f32_16x16x32_bf16 v[36:39], v[172:175], v[200:203], v[36:39]
	v_mfma_f32_16x16x32_bf16 v[32:35], v[180:183], v[200:203], v[32:35]
	v_mfma_f32_16x16x32_bf16 v[20:23], v[172:175], v[208:211], v[20:23]
	v_mfma_f32_16x16x32_bf16 v[16:19], v[180:183], v[208:211], v[16:19]
	v_mfma_f32_16x16x32_bf16 v[4:7], v[172:175], v[216:219], v[4:7]
	v_mfma_f32_16x16x32_bf16 v[0:3], v[180:183], v[216:219], v[0:3]
	s_barrier
	s_add_i32 s8, s8, 2
	s_addk_i32 s2, 0x100
	s_addk_i32 s3, 0x100
	v_add_u32_e32 v134, 0x100, v134
	s_cmp_gt_u32 s8, 13
	v_add_u32_e32 v135, 0x100, v135
	s_cbranch_scc0 .LBB0_188
.Lpeel_done_188:
	s_and_b64 vcc, exec, s[18:19]
	s_cbranch_vccz .LBB0_191
	s_barrier

;     ...
;         const bool has_next = S.next(ui + 1, nxt);
;         const unsigned nA = has_next ? (unsigned)nxt.pm * tstepA : cA, nB = has_next ? (unsigned)nxt.pn * tstepB : cB;
.LBB0_467:
	s_lshl_b32 s40, s39, 19
	s_and_b64 s[0:1], s[6:7], exec
	s_cselect_b32 s0, s40, s43
	s_lshl_b32 s41, s38, 19
	s_and_b64 s[44:45], s[6:7], exec
	v_mov_b32_e32 v0, 0
	s_cselect_b32 s1, s41, s42
	v_add_u32_e32 v132, s43, v143
	v_add_u32_e32 v134, s43, v144
	s_addk_i32 s42, 0x100
	s_addk_i32 s43, 0x100
	s_mov_b32 s44, -2
	ds_read_b128 v[148:151], v145
	ds_read_b128 v[152:155], v145 offset:1024
	ds_read_b128 v[156:159], v145 offset:2048
	ds_read_b128 v[160:163], v145 offset:3072
	ds_read_b128 v[164:167], v146
	ds_read_b128 v[168:171], v146 offset:1024
	ds_read_b128 v[172:175], v146 offset:2048
	ds_read_b128 v[176:179], v146 offset:3072
	s_cmp_eq_u32 s44, 12
	s_cselect_b32 s47, s0, s43
	s_cselect_b32 s46, s1, s42
	s_or_b32 s45, s47, 0x80
	v_mov_b32_e32 v135, v134
	ds_read_b128 v[180:183], v147
	ds_read_b128 v[192:195], v147 offset:1024
	ds_read_b128 v[196:199], v147 offset:2048
	ds_read_b128 v[200:203], v147 offset:3072
	ds_read_b128 v[204:207], v147 offset:4096
	ds_read_b128 v[208:211], v147 offset:5120
	ds_read_b128 v[212:215], v147 offset:6144
	ds_read_b128 v[216:219], v147 offset:7168
	s_add_i32 m0, s22, 0xc000
	s_nop 0
	global_load_lds_dwordx4 v135, s[10:11]
	v_mov_b32_e32 v135, v132
	s_add_i32 m0, s22, 0xe000
	s_nop 0
	global_load_lds_dwordx4 v135, s[10:11]
	s_waitcnt vmcnt(8)
	s_waitcnt lgkmcnt(0)
	s_barrier
	s_waitcnt lgkmcnt(0)
	v_mfma_f32_16x16x32_bf16 v[124:127], v[148:151], v[180:183], 0
	v_mfma_f32_16x16x32_bf16 v[120:123], v[156:159], v[180:183], 0
	v_mfma_f32_16x16x32_bf16 v[108:111], v[148:151], v[196:199], 0
	v_mfma_f32_16x16x32_bf16 v[104:107], v[156:159], v[196:199], 0
	v_mfma_f32_16x16x32_bf16 v[92:95], v[148:151], v[204:207], 0
	v_mfma_f32_16x16x32_bf16 v[88:91], v[156:159], v[204:207], 0
	v_mfma_f32_16x16x32_bf16 v[76:79], v[148:151], v[212:215], 0
	v_mfma_f32_16x16x32_bf16 v[72:75], v[156:159], v[212:215], 0
	v_mfma_f32_16x16x32_bf16 v[124:127], v[152:155], v[192:195], v[124:127]
	v_mfma_f32_16x16x32_bf16 v[120:123], v[160:163], v[192:195], v[120:123]
	v_mfma_f32_16x16x32_bf16 v[108:111], v[152:155], v[200:203], v[108:111]
	v_mfma_f32_16x16x32_bf16 v[104:107], v[160:163], v[200:203], v[104:107]
	v_mfma_f32_16x16x32_bf16 v[92:95], v[152:155], v[208:211], v[92:95]
	v_mfma_f32_16x16x32_bf16 v[88:91], v[160:163], v[208:211], v[88:91]
	v_mfma_f32_16x16x32_bf16 v[76:79], v[152:155], v[216:219], v[76:79]
	v_mfma_f32_16x16x32_bf16 v[72:75], v[160:163], v[216:219], v[72:75]
	v_mfma_f32_16x16x32_bf16 v[116:119], v[164:167], v[180:183], 0
	v_mfma_f32_16x16x32_bf16 v[112:115], v[172:175], v[180:183], 0
	v_mfma_f32_16x16x32_bf16 v[100:103], v[164:167], v[196:199], 0
	v_mfma_f32_16x16x32_bf16 v[96:99], v[172:175], v[196:199], 0
	v_mfma_f32_16x16x32_bf16 v[84:87], v[164:167], v[204:207], 0
	v_mfma_f32_16x16x32_bf16 v[80:83], v[172:175], v[204:207], 0
	v_mfma_f32_16x16x32_bf16 v[68:71], v[164:167], v[212:215], 0
	v_mfma_f32_16x16x32_bf16 v[64:67], v[172:175], v[212:215], 0
	v_mfma_f32_16x16x32_bf16 v[116:119], v[168:171], v[192:195], v[116:119]
	v_mfma_f32_16x16x32_bf16 v[112:115], v[176:179], v[192:195], v[112:115]
	v_mfma_f32_16x16x32_bf16 v[100:103], v[168:171], v[200:203], v[100:103]
	v_mfma_f32_16x16x32_bf16 v[96:99], v[176:179], v[200:203], v[96:99]
	v_mfma_f32_16x16x32_bf16 v[84:87], v[168:171], v[208:211], v[84:87]
	v_mfma_f32_16x16x32_bf16 v[80:83], v[176:179], v[208:211], v[80:83]
	v_mfma_f32_16x16x32_bf16 v[68:71], v[168:171], v[216:219], v[68:71]
	v_mfma_f32_16x16x32_bf16 v[64:67], v[176:179], v[216:219], v[64:67]
	s_barrier
	v_add_u32_e32 v135, s46, v137
	s_add_i32 s48, s35, s19
	ds_read_b128 v[180:183], v147 offset:16384
	ds_read_b128 v[192:195], v147 offset:17408
	ds_read_b128 v[196:199], v147 offset:18432
	ds_read_b128 v[200:203], v147 offset:19456
	ds_read_b128 v[204:207], v147 offset:20480
	ds_read_b128 v[208:211], v147 offset:21504
	ds_read_b128 v[212:215], v147 offset:22528
	ds_read_b128 v[216:219], v147 offset:23552
	s_mov_b32 m0, s48
	s_add_i32 s49, s36, s19
	global_load_lds_dwordx4 v135, s[12:13]
	v_add_u32_e32 v135, s46, v139
	s_add_i32 m0, s48, 0x2000
	s_add_i32 s48, s46, 0x40000
	global_load_lds_dwordx4 v135, s[12:13]
	v_add_u32_e32 v135, s48, v137
	s_mov_b32 m0, s49
	s_nop 0
	global_load_lds_dwordx4 v135, s[12:13]
	v_add_u32_e32 v135, s48, v139
	s_add_i32 m0, s49, 0x2000
	s_nop 0
	global_load_lds_dwordx4 v135, s[12:13]
	v_add_u32_e32 v135, s47, v136
	s_mov_b32 m0, s22
	s_nop 0
	global_load_lds_dwordx4 v135, s[10:11]
	v_add_u32_e32 v135, s47, v138
	s_mov_b32 m0, s23
	s_nop 0
	global_load_lds_dwordx4 v135, s[10:11]
	s_waitcnt vmcnt(8)
	s_waitcnt lgkmcnt(0)
	s_barrier
	s_waitcnt lgkmcnt(0)
	v_mfma_f32_16x16x32_bf16 v[60:63], v[148:151], v[180:183], 0
	v_mfma_f32_16x16x32_bf16 v[56:59], v[156:159], v[180:183], 0
	v_mfma_f32_16x16x32_bf16 v[44:47], v[148:151], v[196:199], 0
	v_mfma_f32_16x16x32_bf16 v[40:43], v[156:159], v[196:199], 0
	v_mfma_f32_16x16x32_bf16 v[28:31], v[148:151], v[204:207], 0
	v_mfma_f32_16x16x32_bf16 v[24:27], v[156:159], v[204:207], 0
	v_mfma_f32_16x16x32_bf16 v[12:15], v[148:151], v[212:215], 0
	v_mfma_f32_16x16x32_bf16 v[8:11], v[156:159], v[212:215], 0
	v_mfma_f32_16x16x32_bf16 v[60:63], v[152:155], v[192:195], v[60:63]
	v_mfma_f32_16x16x32_bf16 v[56:59], v[160:163], v[192:195], v[56:59]
	v_mfma_f32_16x16x32_bf16 v[44:47], v[152:155], v[200:203], v[44:47]
	v_mfma_f32_16x16x32_bf16 v[40:43], v[160:163], v[200:203], v[40:43]
	v_mfma_f32_16x16x32_bf16 v[28:31], v[152:155], v[208:211], v[28:31]
	v_mfma_f32_16x16x32_bf16 v[24:27], v[160:163], v[208:211], v[24:27]
	v_mfma_f32_16x16x32_bf16 v[12:15], v[152:155], v[216:219], v[12:15]
	v_mfma_f32_16x16x32_bf16 v[8:11], v[160:163], v[216:219], v[8:11]
	v_mfma_f32_16x16x32_bf16 v[52:55], v[164:167], v[180:183], 0
	v_mfma_f32_16x16x32_bf16 v[48:51], v[172:175], v[180:183], 0
	v_mfma_f32_16x16x32_bf16 v[36:39], v[164:167], v[196:199], 0
	v_mfma_f32_16x16x32_bf16 v[32:35], v[172:175], v[196:199], 0
	v_mfma_f32_16x16x32_bf16 v[20:23], v[164:167], v[204:207], 0
	v_mfma_f32_16x16x32_bf16 v[16:19], v[172:175], v[204:207], 0
	v_mfma_f32_16x16x32_bf16 v[4:7], v[164:167], v[212:215], 0
	v_mfma_f32_16x16x32_bf16 v[0:3], v[172:175], v[212:215], 0
	v_mfma_f32_16x16x32_bf16 v[52:55], v[168:171], v[192:195], v[52:55]
	v_mfma_f32_16x16x32_bf16 v[48:51], v[176:179], v[192:195], v[48:51]
	v_mfma_f32_16x16x32_bf16 v[36:39], v[168:171], v[200:203], v[36:39]
	v_mfma_f32_16x16x32_bf16 v[32:35], v[176:179], v[200:203], v[32:35]
	v_mfma_f32_16x16x32_bf16 v[20:23], v[168:171], v[208:211], v[20:23]
	v_mfma_f32_16x16x32_bf16 v[16:19], v[176:179], v[208:211], v[16:19]
	v_mfma_f32_16x16x32_bf16 v[4:7], v[168:171], v[216:219], v[4:7]
	v_mfma_f32_16x16x32_bf16 v[0:3], v[176:179], v[216:219], v[0:3]
	s_barrier
	s_add_i32 s48, 0, 0x18000
	v_add_u32_e32 v135, s48, v141
	s_add_i32 s49, 0, 0x1c000
	ds_read_b128 v[148:151], v135
	ds_read_b128 v[152:155], v135 offset:1024
	ds_read_b128 v[156:159], v135 offset:2048
	ds_read_b128 v[160:163], v135 offset:3072
	v_add_u32_e32 v135, s49, v141
	ds_read_b128 v[164:167], v135
	ds_read_b128 v[168:171], v135 offset:1024
	ds_read_b128 v[172:175], v135 offset:2048
	ds_read_b128 v[176:179], v135 offset:3072
	s_add_i32 s47, s47, 0x40000
	v_add_u32_e32 v135, s47, v136
	s_mov_b32 m0, s24
	ds_read_b128 v[180:183], v147 offset:32768
	ds_read_b128 v[192:195], v147 offset:33792
	ds_read_b128 v[196:199], v147 offset:34816
	ds_read_b128 v[200:203], v147 offset:35840
	ds_read_b128 v[204:207], v147 offset:36864
	ds_read_b128 v[208:211], v147 offset:37888
	ds_read_b128 v[212:215], v147 offset:38912
	ds_read_b128 v[216:219], v147 offset:39936
	s_nop 0
	global_load_lds_dwordx4 v135, s[10:11]
	v_add_u32_e32 v135, s47, v138
	s_mov_b32 m0, s25
	s_nop 0
	global_load_lds_dwordx4 v135, s[10:11]
	s_waitcnt vmcnt(8)
	s_waitcnt lgkmcnt(0)
	s_barrier
	s_waitcnt lgkmcnt(0)
	v_mfma_f32_16x16x32_bf16 v[124:127], v[148:151], v[180:183], v[124:127]
	v_mfma_f32_16x16x32_bf16 v[120:123], v[156:159], v[180:183], v[120:123]
	v_mfma_f32_16x16x32_bf16 v[108:111], v[148:151], v[196:199], v[108:111]
	v_mfma_f32_16x16x32_bf16 v[104:107], v[156:159], v[196:199], v[104:107]
	v_mfma_f32_16x16x32_bf16 v[92:95], v[148:151], v[204:207], v[92:95]
	v_mfma_f32_16x16x32_bf16 v[88:91], v[156:159], v[204:207], v[88:91]
	v_mfma_f32_16x16x32_bf16 v[76:79], v[148:151], v[212:215], v[76:79]
	v_mfma_f32_16x16x32_bf16 v[72:75], v[156:159], v[212:215], v[72:75]
	v_mfma_f32_16x16x32_bf16 v[124:127], v[152:155], v[192:195], v[124:127]
	v_mfma_f32_16x16x32_bf16 v[120:123], v[160:163], v[192:195], v[120:123]
	v_mfma_f32_16x16x32_bf16 v[108:111], v[152:155], v[200:203], v[108:111]
	v_mfma_f32_16x16x32_bf16 v[104:107], v[160:163], v[200:203], v[104:107]
	v_mfma_f32_16x16x32_bf16 v[92:95], v[152:155], v[208:211], v[92:95]
	v_mfma_f32_16x16x32_bf16 v[88:91], v[160:163], v[208:211], v[88:91]
	v_mfma_f32_16x16x32_bf16 v[76:79], v[152:155], v[216:219], v[76:79]
	v_mfma_f32_16x16x32_bf16 v[72:75], v[160:163], v[216:219], v[72:75]
	v_mfma_f32_16x16x32_bf16 v[116:119], v[164:167], v[180:183], v[116:119]
	v_mfma_f32_16x16x32_bf16 v[112:115], v[172:175], v[180:183], v[112:115]
	v_mfma_f32_16x16x32_bf16 v[100:103], v[164:167], v[196:199], v[100:103]
	v_mfma_f32_16x16x32_bf16 v[96:99], v[172:175], v[196:199], v[96:99]
	v_mfma_f32_16x16x32_bf16 v[84:87], v[164:167], v[204:207], v[84:87]
	v_mfma_f32_16x16x32_bf16 v[80:83], v[172:175], v[204:207], v[80:83]
	v_mfma_f32_16x16x32_bf16 v[68:71], v[164:167], v[212:215], v[68:71]
	v_mfma_f32_16x16x32_bf16 v[64:67], v[172:175], v[212:215], v[64:67]
	v_mfma_f32_16x16x32_bf16 v[116:119], v[168:171], v[192:195], v[116:119]
	v_mfma_f32_16x16x32_bf16 v[112:115], v[176:179], v[192:195], v[112:115]
	v_mfma_f32_16x16x32_bf16 v[100:103], v[168:171], v[200:203], v[100:103]
	v_mfma_f32_16x16x32_bf16 v[96:99], v[176:179], v[200:203], v[96:99]
	v_mfma_f32_16x16x32_bf16 v[84:87], v[168:171], v[208:211], v[84:87]
	v_mfma_f32_16x16x32_bf16 v[80:83], v[176:179], v[208:211], v[80:83]
	v_mfma_f32_16x16x32_bf16 v[68:71], v[168:171], v[216:219], v[68:71]
	v_mfma_f32_16x16x32_bf16 v[64:67], v[176:179], v[216:219], v[64:67]
	s_barrier
;     ...
;         if constexpr (Epi::MIDHOOK) {
;             for (int t = 0; t < 4; t += 2) PG8_ITER(t);
;             E.mid(acc, cur, wr, wc, fr, fq);
;             for (int t = 4; t < nt; t += 2) PG8_ITER(t);
;         } else {
;             for (int t = 0; t < nt; t += 2) PG8_ITER(t);
	s_or_b32 s47, s46, 0x80
	v_add_u32_e32 v135, s47, v137
	s_add_i32 s48, s48, s19
	ds_read_b128 v[180:183], v147 offset:49152
	ds_read_b128 v[192:195], v147 offset:50176
	ds_read_b128 v[196:199], v147 offset:51200
	ds_read_b128 v[200:203], v147 offset:52224
	ds_read_b128 v[204:207], v147 offset:53248
	ds_read_b128 v[208:211], v147 offset:54272
	ds_read_b128 v[212:215], v147 offset:55296
	ds_read_b128 v[216:219], v147 offset:56320
	s_mov_b32 m0, s48
	s_add_i32 s46, s46, 0x40080
	global_load_lds_dwordx4 v135, s[12:13]
	v_add_u32_e32 v135, s47, v139
	s_add_i32 m0, s48, 0x2000
	s_add_i32 s47, s49, s19
	global_load_lds_dwordx4 v135, s[12:13]
	v_add_u32_e32 v135, s46, v137
	s_mov_b32 m0, s47
	s_nop 0
	global_load_lds_dwordx4 v135, s[12:13]
	v_add_u32_e32 v135, s46, v139
	s_add_i32 m0, s47, 0x2000
	s_nop 0
	global_load_lds_dwordx4 v135, s[12:13]
	v_add_u32_e32 v135, s45, v136
	s_mov_b32 m0, s30
	s_nop 0
	global_load_lds_dwordx4 v135, s[10:11]
	v_add_u32_e32 v135, s45, v138
	s_mov_b32 m0, s31
	s_nop 0
	global_load_lds_dwordx4 v135, s[10:11]
	s_waitcnt vmcnt(8)
	s_waitcnt lgkmcnt(0)
	s_barrier
	s_waitcnt lgkmcnt(0)
	v_mfma_f32_16x16x32_bf16 v[60:63], v[148:151], v[180:183], v[60:63]
	v_mfma_f32_16x16x32_bf16 v[56:59], v[156:159], v[180:183], v[56:59]
	v_mfma_f32_16x16x32_bf16 v[44:47], v[148:151], v[196:199], v[44:47]
	v_mfma_f32_16x16x32_bf16 v[40:43], v[156:159], v[196:199], v[40:43]
	v_mfma_f32_16x16x32_bf16 v[28:31], v[148:151], v[204:207], v[28:31]
	v_mfma_f32_16x16x32_bf16 v[24:27], v[156:159], v[204:207], v[24:27]
	v_mfma_f32_16x16x32_bf16 v[12:15], v[148:151], v[212:215], v[12:15]
	v_mfma_f32_16x16x32_bf16 v[8:11], v[156:159], v[212:215], v[8:11]
	v_mfma_f32_16x16x32_bf16 v[60:63], v[152:155], v[192:195], v[60:63]
	v_mfma_f32_16x16x32_bf16 v[56:59], v[160:163], v[192:195], v[56:59]
	v_mfma_f32_16x16x32_bf16 v[44:47], v[152:155], v[200:203], v[44:47]
	v_mfma_f32_16x16x32_bf16 v[40:43], v[160:163], v[200:203], v[40:43]
	v_mfma_f32_16x16x32_bf16 v[28:31], v[152:155], v[208:211], v[28:31]
	v_mfma_f32_16x16x32_bf16 v[24:27], v[160:163], v[208:211], v[24:27]
	v_mfma_f32_16x16x32_bf16 v[12:15], v[152:155], v[216:219], v[12:15]
	v_mfma_f32_16x16x32_bf16 v[8:11], v[160:163], v[216:219], v[8:11]
	v_mfma_f32_16x16x32_bf16 v[52:55], v[164:167], v[180:183], v[52:55]
	v_mfma_f32_16x16x32_bf16 v[48:51], v[172:175], v[180:183], v[48:51]
	v_mfma_f32_16x16x32_bf16 v[36:39], v[164:167], v[196:199], v[36:39]
	v_mfma_f32_16x16x32_bf16 v[32:35], v[172:175], v[196:199], v[32:35]
	v_mfma_f32_16x16x32_bf16 v[20:23], v[164:167], v[204:207], v[20:23]
	v_mfma_f32_16x16x32_bf16 v[16:19], v[172:175], v[204:207], v[16:19]
	v_mfma_f32_16x16x32_bf16 v[4:7], v[164:167], v[212:215], v[4:7]
	v_mfma_f32_16x16x32_bf16 v[0:3], v[172:175], v[212:215], v[0:3]
	v_mfma_f32_16x16x32_bf16 v[52:55], v[168:171], v[192:195], v[52:55]
	v_mfma_f32_16x16x32_bf16 v[48:51], v[176:179], v[192:195], v[48:51]
	v_mfma_f32_16x16x32_bf16 v[36:39], v[168:171], v[200:203], v[36:39]
	v_mfma_f32_16x16x32_bf16 v[32:35], v[176:179], v[200:203], v[32:35]
	v_mfma_f32_16x16x32_bf16 v[20:23], v[168:171], v[208:211], v[20:23]
	v_mfma_f32_16x16x32_bf16 v[16:19], v[176:179], v[208:211], v[16:19]
	v_mfma_f32_16x16x32_bf16 v[4:7], v[168:171], v[216:219], v[4:7]
	v_mfma_f32_16x16x32_bf16 v[0:3], v[176:179], v[216:219], v[0:3]
	s_barrier
	s_add_i32 s44, s44, 2
	s_addk_i32 s42, 0x100
	s_addk_i32 s43, 0x100
	v_add_u32_e32 v132, 0x100, v132
	s_cmp_gt_u32 s44, 13
	v_add_u32_e32 v134, 0x100, v134
	s_cbranch_scc1 .Lpeel_done_468
.LBB0_468:
	ds_read_b128 v[148:151], v145
	ds_read_b128 v[152:155], v145 offset:1024
	ds_read_b128 v[156:159], v145 offset:2048
	ds_read_b128 v[160:163], v145 offset:3072
	ds_read_b128 v[164:167], v146
	ds_read_b128 v[168:171], v146 offset:1024
	ds_read_b128 v[172:175], v146 offset:2048
	ds_read_b128 v[176:179], v146 offset:3072
	s_cmp_eq_u32 s44, 12
	s_cselect_b32 s47, s0, s43
	s_cselect_b32 s46, s1, s42
	s_or_b32 s45, s47, 0x80
	v_mov_b32_e32 v135, v134
	ds_read_b128 v[180:183], v147
	ds_read_b128 v[192:195], v147 offset:1024
	ds_read_b128 v[196:199], v147 offset:2048
	ds_read_b128 v[200:203], v147 offset:3072
	ds_read_b128 v[204:207], v147 offset:4096
	ds_read_b128 v[208:211], v147 offset:5120
	ds_read_b128 v[212:215], v147 offset:6144
	ds_read_b128 v[216:219], v147 offset:7168
	s_add_i32 m0, s22, 0xc000
	s_nop 0
	global_load_lds_dwordx4 v135, s[10:11]
	v_mov_b32_e32 v135, v132
	s_add_i32 m0, s22, 0xe000
	s_nop 0
	global_load_lds_dwordx4 v135, s[10:11]
	s_waitcnt vmcnt(8)
	s_waitcnt lgkmcnt(0)
	s_barrier
	s_waitcnt lgkmcnt(0)
	v_mfma_f32_16x16x32_bf16 v[124:127], v[148:151], v[180:183], v[124:127]
	v_mfma_f32_16x16x32_bf16 v[120:123], v[156:159], v[180:183], v[120:123]
	v_mfma_f32_16x16x32_bf16 v[108:111], v[148:151], v[196:199], v[108:111]
	v_mfma_f32_16x16x32_bf16 v[104:107], v[156:159], v[196:199], v[104:107]
	v_mfma_f32_16x16x32_bf16 v[92:95], v[148:151], v[204:207], v[92:95]
	v_mfma_f32_16x16x32_bf16 v[88:91], v[156:159], v[204:207], v[88:91]
	v_mfma_f32_16x16x32_bf16 v[76:79], v[148:151], v[212:215], v[76:79]
	v_mfma_f32_16x16x32_bf16 v[72:75], v[156:159], v[212:215], v[72:75]
	v_mfma_f32_16x16x32_bf16 v[124:127], v[152:155], v[192:195], v[124:127]
	v_mfma_f32_16x16x32_bf16 v[120:123], v[160:163], v[192:195], v[120:123]
	v_mfma_f32_16x16x32_bf16 v[108:111], v[152:155], v[200:203], v[108:111]
	v_mfma_f32_16x16x32_bf16 v[104:107], v[160:163], v[200:203], v[104:107]
	v_mfma_f32_16x16x32_bf16 v[92:95], v[152:155], v[208:211], v[92:95]
	v_mfma_f32_16x16x32_bf16 v[88:91], v[160:163], v[208:211], v[88:91]
	v_mfma_f32_16x16x32_bf16 v[76:79], v[152:155], v[216:219], v[76:79]
	v_mfma_f32_16x16x32_bf16 v[72:75], v[160:163], v[216:219], v[72:75]
	v_mfma_f32_16x16x32_bf16 v[116:119], v[164:167], v[180:183], v[116:119]
	v_mfma_f32_16x16x32_bf16 v[112:115], v[172:175], v[180:183], v[112:115]
	v_mfma_f32_16x16x32_bf16 v[100:103], v[164:167], v[196:199], v[100:103]
	v_mfma_f32_16x16x32_bf16 v[96:99], v[172:175], v[196:199], v[96:99]
	v_mfma_f32_16x16x32_bf16 v[84:87], v[164:167], v[204:207], v[84:87]
	v_mfma_f32_16x16x32_bf16 v[80:83], v[172:175], v[204:207], v[80:83]
	v_mfma_f32_16x16x32_bf16 v[68:71], v[164:167], v[212:215], v[68:71]
	v_mfma_f32_16x16x32_bf16 v[64:67], v[172:175], v[212:215], v[64:67]
	v_mfma_f32_16x16x32_bf16 v[116:119], v[168:171], v[192:195], v[116:119]
	v_mfma_f32_16x16x32_bf16 v[112:115], v[176:179], v[192:195], v[112:115]
	v_mfma_f32_16x16x32_bf16 v[100:103], v[168:171], v[200:203], v[100:103]
	v_mfma_f32_16x16x32_bf16 v[96:99], v[176:179], v[200:203], v[96:99]
	v_mfma_f32_16x16x32_bf16 v[84:87], v[168:171], v[208:211], v[84:87]
	v_mfma_f32_16x16x32_bf16 v[80:83], v[176:179], v[208:211], v[80:83]
	v_mfma_f32_16x16x32_bf16 v[68:71], v[168:171], v[216:219], v[68:71]
	v_mfma_f32_16x16x32_bf16 v[64:67], v[176:179], v[216:219], v[64:67]
	s_barrier
	v_add_u32_e32 v135, s46, v137
	s_add_i32 s48, s35, s19
	ds_read_b128 v[180:183], v147 offset:16384
	ds_read_b128 v[192:195], v147 offset:17408
	ds_read_b128 v[196:199], v147 offset:18432
	ds_read_b128 v[200:203], v147 offset:19456
	ds_read_b128 v[204:207], v147 offset:20480
	ds_read_b128 v[208:211], v147 offset:21504
	ds_read_b128 v[212:215], v147 offset:22528
	ds_read_b128 v[216:219], v147 offset:23552
	s_mov_b32 m0, s48
	s_add_i32 s49, s36, s19
	global_load_lds_dwordx4 v135, s[12:13]
	v_add_u32_e32 v135, s46, v139
	s_add_i32 m0, s48, 0x2000
	s_add_i32 s48, s46, 0x40000
	global_load_lds_dwordx4 v135, s[12:13]
	v_add_u32_e32 v135, s48, v137
	s_mov_b32 m0, s49
	s_nop 0
	global_load_lds_dwordx4 v135, s[12:13]
	v_add_u32_e32 v135, s48, v139
	s_add_i32 m0, s49, 0x2000
	s_nop 0
	global_load_lds_dwordx4 v135, s[12:13]
	v_add_u32_e32 v135, s47, v136
	s_mov_b32 m0, s22
	s_nop 0
	global_load_lds_dwordx4 v135, s[10:11]
	v_add_u32_e32 v135, s47, v138
	s_mov_b32 m0, s23
	s_nop 0
	global_load_lds_dwordx4 v135, s[10:11]
	s_waitcnt vmcnt(8)
	s_waitcnt lgkmcnt(0)
	s_barrier
	s_waitcnt lgkmcnt(0)
	v_mfma_f32_16x16x32_bf16 v[60:63], v[148:151], v[180:183], v[60:63]
	v_mfma_f32_16x16x32_bf16 v[56:59], v[156:159], v[180:183], v[56:59]
	v_mfma_f32_16x16x32_bf16 v[44:47], v[148:151], v[196:199], v[44:47]
	v_mfma_f32_16x16x32_bf16 v[40:43], v[156:159], v[196:199], v[40:43]
	v_mfma_f32_16x16x32_bf16 v[28:31], v[148:151], v[204:207], v[28:31]
	v_mfma_f32_16x16x32_bf16 v[24:27], v[156:159], v[204:207], v[24:27]
	v_mfma_f32_16x16x32_bf16 v[12:15], v[148:151], v[212:215], v[12:15]
	v_mfma_f32_16x16x32_bf16 v[8:11], v[156:159], v[212:215], v[8:11]
	v_mfma_f32_16x16x32_bf16 v[60:63], v[152:155], v[192:195], v[60:63]
	v_mfma_f32_16x16x32_bf16 v[56:59], v[160:163], v[192:195], v[56:59]
	v_mfma_f32_16x16x32_bf16 v[44:47], v[152:155], v[200:203], v[44:47]
	v_mfma_f32_16x16x32_bf16 v[40:43], v[160:163], v[200:203], v[40:43]
	v_mfma_f32_16x16x32_bf16 v[28:31], v[152:155], v[208:211], v[28:31]
	v_mfma_f32_16x16x32_bf16 v[24:27], v[160:163], v[208:211], v[24:27]
	v_mfma_f32_16x16x32_bf16 v[12:15], v[152:155], v[216:219], v[12:15]
	v_mfma_f32_16x16x32_bf16 v[8:11], v[160:163], v[216:219], v[8:11]
	v_mfma_f32_16x16x32_bf16 v[52:55], v[164:167], v[180:183], v[52:55]
	v_mfma_f32_16x16x32_bf16 v[48:51], v[172:175], v[180:183], v[48:51]
	v_mfma_f32_16x16x32_bf16 v[36:39], v[164:167], v[196:199], v[36:39]
	v_mfma_f32_16x16x32_bf16 v[32:35], v[172:175], v[196:199], v[32:35]
	v_mfma_f32_16x16x32_bf16 v[20:23], v[164:167], v[204:207], v[20:23]
	v_mfma_f32_16x16x32_bf16 v[16:19], v[172:175], v[204:207], v[16:19]
	v_mfma_f32_16x16x32_bf16 v[4:7], v[164:167], v[212:215], v[4:7]
	v_mfma_f32_16x16x32_bf16 v[0:3], v[172:175], v[212:215], v[0:3]
	v_mfma_f32_16x16x32_bf16 v[52:55], v[168:171], v[192:195], v[52:55]
	v_mfma_f32_16x16x32_bf16 v[48:51], v[176:179], v[192:195], v[48:51]
	v_mfma_f32_16x16x32_bf16 v[36:39], v[168:171], v[200:203], v[36:39]
	v_mfma_f32_16x16x32_bf16 v[32:35], v[176:179], v[200:203], v[32:35]
	v_mfma_f32_16x16x32_bf16 v[20:23], v[168:171], v[208:211], v[20:23]
	v_mfma_f32_16x16x32_bf16 v[16:19], v[176:179], v[208:211], v[16:19]
	v_mfma_f32_16x16x32_bf16 v[4:7], v[168:171], v[216:219], v[4:7]
	v_mfma_f32_16x16x32_bf16 v[0:3], v[176:179], v[216:219], v[0:3]
	s_barrier
; #define PG8_BAR __builtin_amdgcn_s_barrier()
;     ...
;         if constexpr (Epi::MIDHOOK) {
;             for (int t = 0; t < 4; t += 2) PG8_ITER(t);
;             E.mid(acc, cur, wr, wc, fr, fq);
;             for (int t = 4; t < nt; t += 2) PG8_ITER(t);
;         } else {
;             for (int t = 0; t < nt; t += 2) PG8_ITER(t);
;         }
;     ...
;         if constexpr (ALIGN_EPI) { if (wr == 0) PG8_BAR; }
	s_add_i32 s48, 0, 0x18000
	v_add_u32_e32 v135, s48, v141
	s_add_i32 s49, 0, 0x1c000
	ds_read_b128 v[148:151], v135
	ds_read_b128 v[152:155], v135 offset:1024
	ds_read_b128 v[156:159], v135 offset:2048
	ds_read_b128 v[160:163], v135 offset:3072
	v_add_u32_e32 v135, s49, v141
	ds_read_b128 v[164:167], v135
	ds_read_b128 v[168:171], v135 offset:1024
	ds_read_b128 v[172:175], v135 offset:2048
	ds_read_b128 v[176:179], v135 offset:3072
	s_add_i32 s47, s47, 0x40000
	v_add_u32_e32 v135, s47, v136
	s_mov_b32 m0, s24
	ds_read_b128 v[180:183], v147 offset:32768
	ds_read_b128 v[192:195], v147 offset:33792
	ds_read_b128 v[196:199], v147 offset:34816
	ds_read_b128 v[200:203], v147 offset:35840
	ds_read_b128 v[204:207], v147 offset:36864
	ds_read_b128 v[208:211], v147 offset:37888
	ds_read_b128 v[212:215], v147 offset:38912
	ds_read_b128 v[216:219], v147 offset:39936
	s_nop 0
	global_load_lds_dwordx4 v135, s[10:11]
	v_add_u32_e32 v135, s47, v138
	s_mov_b32 m0, s25
	s_nop 0
	global_load_lds_dwordx4 v135, s[10:11]
	s_waitcnt vmcnt(8)
	s_waitcnt lgkmcnt(0)
	s_barrier
	s_waitcnt lgkmcnt(0)
	v_mfma_f32_16x16x32_bf16 v[124:127], v[148:151], v[180:183], v[124:127]
	v_mfma_f32_16x16x32_bf16 v[120:123], v[156:159], v[180:183], v[120:123]
	v_mfma_f32_16x16x32_bf16 v[108:111], v[148:151], v[196:199], v[108:111]
	v_mfma_f32_16x16x32_bf16 v[104:107], v[156:159], v[196:199], v[104:107]
	v_mfma_f32_16x16x32_bf16 v[92:95], v[148:151], v[204:207], v[92:95]
	v_mfma_f32_16x16x32_bf16 v[88:91], v[156:159], v[204:207], v[88:91]
	v_mfma_f32_16x16x32_bf16 v[76:79], v[148:151], v[212:215], v[76:79]
	v_mfma_f32_16x16x32_bf16 v[72:75], v[156:159], v[212:215], v[72:75]
	v_mfma_f32_16x16x32_bf16 v[124:127], v[152:155], v[192:195], v[124:127]
	v_mfma_f32_16x16x32_bf16 v[120:123], v[160:163], v[192:195], v[120:123]
	v_mfma_f32_16x16x32_bf16 v[108:111], v[152:155], v[200:203], v[108:111]
	v_mfma_f32_16x16x32_bf16 v[104:107], v[160:163], v[200:203], v[104:107]
	v_mfma_f32_16x16x32_bf16 v[92:95], v[152:155], v[208:211], v[92:95]
	v_mfma_f32_16x16x32_bf16 v[88:91], v[160:163], v[208:211], v[88:91]
	v_mfma_f32_16x16x32_bf16 v[76:79], v[152:155], v[216:219], v[76:79]
	v_mfma_f32_16x16x32_bf16 v[72:75], v[160:163], v[216:219], v[72:75]
	v_mfma_f32_16x16x32_bf16 v[116:119], v[164:167], v[180:183], v[116:119]
	v_mfma_f32_16x16x32_bf16 v[112:115], v[172:175], v[180:183], v[112:115]
	v_mfma_f32_16x16x32_bf16 v[100:103], v[164:167], v[196:199], v[100:103]
	v_mfma_f32_16x16x32_bf16 v[96:99], v[172:175], v[196:199], v[96:99]
	v_mfma_f32_16x16x32_bf16 v[84:87], v[164:167], v[204:207], v[84:87]
	v_mfma_f32_16x16x32_bf16 v[80:83], v[172:175], v[204:207], v[80:83]
	v_mfma_f32_16x16x32_bf16 v[68:71], v[164:167], v[212:215], v[68:71]
	v_mfma_f32_16x16x32_bf16 v[64:67], v[172:175], v[212:215], v[64:67]
	v_mfma_f32_16x16x32_bf16 v[116:119], v[168:171], v[192:195], v[116:119]
	v_mfma_f32_16x16x32_bf16 v[112:115], v[176:179], v[192:195], v[112:115]
	v_mfma_f32_16x16x32_bf16 v[100:103], v[168:171], v[200:203], v[100:103]
	v_mfma_f32_16x16x32_bf16 v[96:99], v[176:179], v[200:203], v[96:99]
	v_mfma_f32_16x16x32_bf16 v[84:87], v[168:171], v[208:211], v[84:87]
	v_mfma_f32_16x16x32_bf16 v[80:83], v[176:179], v[208:211], v[80:83]
	v_mfma_f32_16x16x32_bf16 v[68:71], v[168:171], v[216:219], v[68:71]
	v_mfma_f32_16x16x32_bf16 v[64:67], v[176:179], v[216:219], v[64:67]
	s_barrier
	s_or_b32 s47, s46, 0x80
	v_add_u32_e32 v135, s47, v137
	s_add_i32 s48, s48, s19
	ds_read_b128 v[180:183], v147 offset:49152
	ds_read_b128 v[192:195], v147 offset:50176
	ds_read_b128 v[196:199], v147 offset:51200
	ds_read_b128 v[200:203], v147 offset:52224
	ds_read_b128 v[204:207], v147 offset:53248
	ds_read_b128 v[208:211], v147 offset:54272
	ds_read_b128 v[212:215], v147 offset:55296
	ds_read_b128 v[216:219], v147 offset:56320
	s_mov_b32 m0, s48
	s_add_i32 s46, s46, 0x40080
	global_load_lds_dwordx4 v135, s[12:13]
	v_add_u32_e32 v135, s47, v139
	s_add_i32 m0, s48, 0x2000
	s_add_i32 s47, s49, s19
	global_load_lds_dwordx4 v135, s[12:13]
	v_add_u32_e32 v135, s46, v137
	s_mov_b32 m0, s47
	s_nop 0
	global_load_lds_dwordx4 v135, s[12:13]
	v_add_u32_e32 v135, s46, v139
	s_add_i32 m0, s47, 0x2000
	s_nop 0
	global_load_lds_dwordx4 v135, s[12:13]
	v_add_u32_e32 v135, s45, v136
	s_mov_b32 m0, s30
	s_nop 0
	global_load_lds_dwordx4 v135, s[10:11]
	v_add_u32_e32 v135, s45, v138
	s_mov_b32 m0, s31
	s_nop 0
	global_load_lds_dwordx4 v135, s[10:11]
	s_waitcnt vmcnt(8)
	s_waitcnt lgkmcnt(0)
	s_barrier
	s_waitcnt lgkmcnt(0)
	v_mfma_f32_16x16x32_bf16 v[60:63], v[148:151], v[180:183], v[60:63]
	v_mfma_f32_16x16x32_bf16 v[56:59], v[156:159], v[180:183], v[56:59]
	v_mfma_f32_16x16x32_bf16 v[44:47], v[148:151], v[196:199], v[44:47]
	v_mfma_f32_16x16x32_bf16 v[40:43], v[156:159], v[196:199], v[40:43]
	v_mfma_f32_16x16x32_bf16 v[28:31], v[148:151], v[204:207], v[28:31]
	v_mfma_f32_16x16x32_bf16 v[24:27], v[156:159], v[204:207], v[24:27]
	v_mfma_f32_16x16x32_bf16 v[12:15], v[148:151], v[212:215], v[12:15]
	v_mfma_f32_16x16x32_bf16 v[8:11], v[156:159], v[212:215], v[8:11]
	v_mfma_f32_16x16x32_bf16 v[60:63], v[152:155], v[192:195], v[60:63]
	v_mfma_f32_16x16x32_bf16 v[56:59], v[160:163], v[192:195], v[56:59]
	v_mfma_f32_16x16x32_bf16 v[44:47], v[152:155], v[200:203], v[44:47]
	v_mfma_f32_16x16x32_bf16 v[40:43], v[160:163], v[200:203], v[40:43]
	v_mfma_f32_16x16x32_bf16 v[28:31], v[152:155], v[208:211], v[28:31]
	v_mfma_f32_16x16x32_bf16 v[24:27], v[160:163], v[208:211], v[24:27]
	v_mfma_f32_16x16x32_bf16 v[12:15], v[152:155], v[216:219], v[12:15]
	v_mfma_f32_16x16x32_bf16 v[8:11], v[160:163], v[216:219], v[8:11]
	v_mfma_f32_16x16x32_bf16 v[52:55], v[164:167], v[180:183], v[52:55]
	v_mfma_f32_16x16x32_bf16 v[48:51], v[172:175], v[180:183], v[48:51]
	v_mfma_f32_16x16x32_bf16 v[36:39], v[164:167], v[196:199], v[36:39]
	v_mfma_f32_16x16x32_bf16 v[32:35], v[172:175], v[196:199], v[32:35]
	v_mfma_f32_16x16x32_bf16 v[20:23], v[164:167], v[204:207], v[20:23]
	v_mfma_f32_16x16x32_bf16 v[16:19], v[172:175], v[204:207], v[16:19]
	v_mfma_f32_16x16x32_bf16 v[4:7], v[164:167], v[212:215], v[4:7]
	v_mfma_f32_16x16x32_bf16 v[0:3], v[172:175], v[212:215], v[0:3]
	v_mfma_f32_16x16x32_bf16 v[52:55], v[168:171], v[192:195], v[52:55]
	v_mfma_f32_16x16x32_bf16 v[48:51], v[176:179], v[192:195], v[48:51]
	v_mfma_f32_16x16x32_bf16 v[36:39], v[168:171], v[200:203], v[36:39]
	v_mfma_f32_16x16x32_bf16 v[32:35], v[176:179], v[200:203], v[32:35]
	v_mfma_f32_16x16x32_bf16 v[20:23], v[168:171], v[208:211], v[20:23]
	v_mfma_f32_16x16x32_bf16 v[16:19], v[176:179], v[208:211], v[16:19]
	v_mfma_f32_16x16x32_bf16 v[4:7], v[168:171], v[216:219], v[4:7]
	v_mfma_f32_16x16x32_bf16 v[0:3], v[176:179], v[216:219], v[0:3]
	s_barrier
	s_add_i32 s44, s44, 2
	s_addk_i32 s42, 0x100
	s_addk_i32 s43, 0x100
	v_add_u32_e32 v132, 0x100, v132
	s_cmp_gt_u32 s44, 13
	v_add_u32_e32 v134, 0x100, v134
	s_cbranch_scc0 .LBB0_468
.Lpeel_done_468:
	s_and_b64 vcc, exec, s[16:17]
	s_cbranch_vccz .LBB0_471
	s_barrier

;     ...
;         const bool has_next = S.next(ui + 1, nxt);
;         const unsigned nA = has_next ? (unsigned)nxt.pm * tstepA : cA, nB = has_next ? (unsigned)nxt.pn * tstepB : cB;
.LBB0_522:
	s_lshl_b32 s36, s35, 19
	s_and_b64 s[0:1], s[4:5], exec
	s_cselect_b32 s0, s36, s39
	s_lshl_b32 s37, s34, 19
	s_and_b64 s[40:41], s[4:5], exec
	v_mov_b32_e32 v0, 0
	s_cselect_b32 s1, s37, s38
	v_add_u32_e32 v132, s39, v143
	v_add_u32_e32 v134, s39, v144
	s_addk_i32 s38, 0x100
	s_addk_i32 s39, 0x100
	s_mov_b32 s40, -2
	ds_read_b128 v[148:151], v145
	ds_read_b128 v[152:155], v145 offset:1024
	ds_read_b128 v[156:159], v145 offset:2048
	ds_read_b128 v[160:163], v145 offset:3072
	ds_read_b128 v[164:167], v146
	ds_read_b128 v[168:171], v146 offset:1024
	ds_read_b128 v[172:175], v146 offset:2048
	ds_read_b128 v[176:179], v146 offset:3072
	s_cmp_eq_u32 s40, 12
	s_cselect_b32 s43, s0, s39
	s_cselect_b32 s42, s1, s38
	s_or_b32 s41, s43, 0x80
	v_mov_b32_e32 v135, v134
	ds_read_b128 v[180:183], v147
	ds_read_b128 v[192:195], v147 offset:1024
	ds_read_b128 v[196:199], v147 offset:2048
	ds_read_b128 v[200:203], v147 offset:3072
	ds_read_b128 v[204:207], v147 offset:4096
	ds_read_b128 v[208:211], v147 offset:5120
	ds_read_b128 v[212:215], v147 offset:6144
	ds_read_b128 v[216:219], v147 offset:7168
	s_add_i32 m0, s18, 0xc000
	s_nop 0
	global_load_lds_dwordx4 v135, s[8:9]
	v_mov_b32_e32 v135, v132
	s_add_i32 m0, s18, 0xe000
	s_nop 0
	global_load_lds_dwordx4 v135, s[8:9]
	s_waitcnt vmcnt(8)
	s_waitcnt lgkmcnt(0)
	s_barrier
	s_waitcnt lgkmcnt(0)
	v_mfma_f32_16x16x32_bf16 v[124:127], v[148:151], v[180:183], 0
	v_mfma_f32_16x16x32_bf16 v[120:123], v[156:159], v[180:183], 0
	v_mfma_f32_16x16x32_bf16 v[108:111], v[148:151], v[196:199], 0
	v_mfma_f32_16x16x32_bf16 v[104:107], v[156:159], v[196:199], 0
	v_mfma_f32_16x16x32_bf16 v[92:95], v[148:151], v[204:207], 0
	v_mfma_f32_16x16x32_bf16 v[88:91], v[156:159], v[204:207], 0
	v_mfma_f32_16x16x32_bf16 v[76:79], v[148:151], v[212:215], 0
	v_mfma_f32_16x16x32_bf16 v[72:75], v[156:159], v[212:215], 0
	v_mfma_f32_16x16x32_bf16 v[124:127], v[152:155], v[192:195], v[124:127]
	v_mfma_f32_16x16x32_bf16 v[120:123], v[160:163], v[192:195], v[120:123]
	v_mfma_f32_16x16x32_bf16 v[108:111], v[152:155], v[200:203], v[108:111]
	v_mfma_f32_16x16x32_bf16 v[104:107], v[160:163], v[200:203], v[104:107]
	v_mfma_f32_16x16x32_bf16 v[92:95], v[152:155], v[208:211], v[92:95]
	v_mfma_f32_16x16x32_bf16 v[88:91], v[160:163], v[208:211], v[88:91]
	v_mfma_f32_16x16x32_bf16 v[76:79], v[152:155], v[216:219], v[76:79]
	v_mfma_f32_16x16x32_bf16 v[72:75], v[160:163], v[216:219], v[72:75]
	v_mfma_f32_16x16x32_bf16 v[116:119], v[164:167], v[180:183], 0
	v_mfma_f32_16x16x32_bf16 v[112:115], v[172:175], v[180:183], 0
	v_mfma_f32_16x16x32_bf16 v[100:103], v[164:167], v[196:199], 0
	v_mfma_f32_16x16x32_bf16 v[96:99], v[172:175], v[196:199], 0
	v_mfma_f32_16x16x32_bf16 v[84:87], v[164:167], v[204:207], 0
	v_mfma_f32_16x16x32_bf16 v[80:83], v[172:175], v[204:207], 0
	v_mfma_f32_16x16x32_bf16 v[68:71], v[164:167], v[212:215], 0
	v_mfma_f32_16x16x32_bf16 v[64:67], v[172:175], v[212:215], 0
	v_mfma_f32_16x16x32_bf16 v[116:119], v[168:171], v[192:195], v[116:119]
	v_mfma_f32_16x16x32_bf16 v[112:115], v[176:179], v[192:195], v[112:115]
	v_mfma_f32_16x16x32_bf16 v[100:103], v[168:171], v[200:203], v[100:103]
	v_mfma_f32_16x16x32_bf16 v[96:99], v[176:179], v[200:203], v[96:99]
	v_mfma_f32_16x16x32_bf16 v[84:87], v[168:171], v[208:211], v[84:87]
	v_mfma_f32_16x16x32_bf16 v[80:83], v[176:179], v[208:211], v[80:83]
	v_mfma_f32_16x16x32_bf16 v[68:71], v[168:171], v[216:219], v[68:71]
	v_mfma_f32_16x16x32_bf16 v[64:67], v[176:179], v[216:219], v[64:67]
	s_barrier
	v_add_u32_e32 v135, s42, v137
	s_add_i32 s44, s30, s17
	ds_read_b128 v[180:183], v147 offset:16384
	ds_read_b128 v[192:195], v147 offset:17408
	ds_read_b128 v[196:199], v147 offset:18432
	ds_read_b128 v[200:203], v147 offset:19456
	ds_read_b128 v[204:207], v147 offset:20480
	ds_read_b128 v[208:211], v147 offset:21504
	ds_read_b128 v[212:215], v147 offset:22528
	ds_read_b128 v[216:219], v147 offset:23552
	s_mov_b32 m0, s44
	s_add_i32 s45, s31, s17
	global_load_lds_dwordx4 v135, s[10:11]
	v_add_u32_e32 v135, s42, v139
	s_add_i32 m0, s44, 0x2000
	s_add_i32 s44, s42, 0x40000
	global_load_lds_dwordx4 v135, s[10:11]
	v_add_u32_e32 v135, s44, v137
	s_mov_b32 m0, s45
	s_nop 0
	global_load_lds_dwordx4 v135, s[10:11]
	v_add_u32_e32 v135, s44, v139
	s_add_i32 m0, s45, 0x2000
	s_nop 0
	global_load_lds_dwordx4 v135, s[10:11]
	v_add_u32_e32 v135, s43, v136
	s_mov_b32 m0, s18
	s_nop 0
	global_load_lds_dwordx4 v135, s[8:9]
	v_add_u32_e32 v135, s43, v138
	s_mov_b32 m0, s19
	s_nop 0
	global_load_lds_dwordx4 v135, s[8:9]
	s_waitcnt vmcnt(8)
	s_waitcnt lgkmcnt(0)
	s_barrier
	s_waitcnt lgkmcnt(0)
	v_mfma_f32_16x16x32_bf16 v[60:63], v[148:151], v[180:183], 0
	v_mfma_f32_16x16x32_bf16 v[56:59], v[156:159], v[180:183], 0
	v_mfma_f32_16x16x32_bf16 v[44:47], v[148:151], v[196:199], 0
	v_mfma_f32_16x16x32_bf16 v[40:43], v[156:159], v[196:199], 0
	v_mfma_f32_16x16x32_bf16 v[28:31], v[148:151], v[204:207], 0
	v_mfma_f32_16x16x32_bf16 v[24:27], v[156:159], v[204:207], 0
	v_mfma_f32_16x16x32_bf16 v[12:15], v[148:151], v[212:215], 0
	v_mfma_f32_16x16x32_bf16 v[8:11], v[156:159], v[212:215], 0
	v_mfma_f32_16x16x32_bf16 v[60:63], v[152:155], v[192:195], v[60:63]
	v_mfma_f32_16x16x32_bf16 v[56:59], v[160:163], v[192:195], v[56:59]
	v_mfma_f32_16x16x32_bf16 v[44:47], v[152:155], v[200:203], v[44:47]
	v_mfma_f32_16x16x32_bf16 v[40:43], v[160:163], v[200:203], v[40:43]
	v_mfma_f32_16x16x32_bf16 v[28:31], v[152:155], v[208:211], v[28:31]
	v_mfma_f32_16x16x32_bf16 v[24:27], v[160:163], v[208:211], v[24:27]
	v_mfma_f32_16x16x32_bf16 v[12:15], v[152:155], v[216:219], v[12:15]
	v_mfma_f32_16x16x32_bf16 v[8:11], v[160:163], v[216:219], v[8:11]
	v_mfma_f32_16x16x32_bf16 v[52:55], v[164:167], v[180:183], 0
	v_mfma_f32_16x16x32_bf16 v[48:51], v[172:175], v[180:183], 0
	v_mfma_f32_16x16x32_bf16 v[36:39], v[164:167], v[196:199], 0
	v_mfma_f32_16x16x32_bf16 v[32:35], v[172:175], v[196:199], 0
	v_mfma_f32_16x16x32_bf16 v[20:23], v[164:167], v[204:207], 0
	v_mfma_f32_16x16x32_bf16 v[16:19], v[172:175], v[204:207], 0
	v_mfma_f32_16x16x32_bf16 v[4:7], v[164:167], v[212:215], 0
	v_mfma_f32_16x16x32_bf16 v[0:3], v[172:175], v[212:215], 0
	v_mfma_f32_16x16x32_bf16 v[52:55], v[168:171], v[192:195], v[52:55]
	v_mfma_f32_16x16x32_bf16 v[48:51], v[176:179], v[192:195], v[48:51]
	v_mfma_f32_16x16x32_bf16 v[36:39], v[168:171], v[200:203], v[36:39]
	v_mfma_f32_16x16x32_bf16 v[32:35], v[176:179], v[200:203], v[32:35]
	v_mfma_f32_16x16x32_bf16 v[20:23], v[168:171], v[208:211], v[20:23]
	v_mfma_f32_16x16x32_bf16 v[16:19], v[176:179], v[208:211], v[16:19]
	v_mfma_f32_16x16x32_bf16 v[4:7], v[168:171], v[216:219], v[4:7]
	v_mfma_f32_16x16x32_bf16 v[0:3], v[176:179], v[216:219], v[0:3]
	s_barrier
;     ...
;         if constexpr (Epi::MIDHOOK) {
;             for (int t = 0; t < 4; t += 2) PG8_ITER(t);
;             E.mid(acc, cur, wr, wc, fr, fq);
;             for (int t = 4; t < nt; t += 2) PG8_ITER(t);
;         } else {
;             for (int t = 0; t < nt; t += 2) PG8_ITER(t);
	s_add_i32 s44, 0, 0x18000
	v_add_u32_e32 v135, s44, v141
	s_add_i32 s45, 0, 0x1c000
	ds_read_b128 v[148:151], v135
	ds_read_b128 v[152:155], v135 offset:1024
	ds_read_b128 v[156:159], v135 offset:2048
	ds_read_b128 v[160:163], v135 offset:3072
	v_add_u32_e32 v135, s45, v141
	ds_read_b128 v[164:167], v135
	ds_read_b128 v[168:171], v135 offset:1024
	ds_read_b128 v[172:175], v135 offset:2048
	ds_read_b128 v[176:179], v135 offset:3072
	s_add_i32 s43, s43, 0x40000
	v_add_u32_e32 v135, s43, v136
	s_mov_b32 m0, s20
	ds_read_b128 v[180:183], v147 offset:32768
	ds_read_b128 v[192:195], v147 offset:33792
	ds_read_b128 v[196:199], v147 offset:34816
	ds_read_b128 v[200:203], v147 offset:35840
	ds_read_b128 v[204:207], v147 offset:36864
	ds_read_b128 v[208:211], v147 offset:37888
	ds_read_b128 v[212:215], v147 offset:38912
	ds_read_b128 v[216:219], v147 offset:39936
	s_nop 0
	global_load_lds_dwordx4 v135, s[8:9]
	v_add_u32_e32 v135, s43, v138
	s_mov_b32 m0, s21
	s_nop 0
	global_load_lds_dwordx4 v135, s[8:9]
	s_waitcnt vmcnt(8)
	s_waitcnt lgkmcnt(0)
	s_barrier
	s_waitcnt lgkmcnt(0)
	v_mfma_f32_16x16x32_bf16 v[124:127], v[148:151], v[180:183], v[124:127]
	v_mfma_f32_16x16x32_bf16 v[120:123], v[156:159], v[180:183], v[120:123]
	v_mfma_f32_16x16x32_bf16 v[108:111], v[148:151], v[196:199], v[108:111]
	v_mfma_f32_16x16x32_bf16 v[104:107], v[156:159], v[196:199], v[104:107]
	v_mfma_f32_16x16x32_bf16 v[92:95], v[148:151], v[204:207], v[92:95]
	v_mfma_f32_16x16x32_bf16 v[88:91], v[156:159], v[204:207], v[88:91]
	v_mfma_f32_16x16x32_bf16 v[76:79], v[148:151], v[212:215], v[76:79]
	v_mfma_f32_16x16x32_bf16 v[72:75], v[156:159], v[212:215], v[72:75]
	v_mfma_f32_16x16x32_bf16 v[124:127], v[152:155], v[192:195], v[124:127]
	v_mfma_f32_16x16x32_bf16 v[120:123], v[160:163], v[192:195], v[120:123]
	v_mfma_f32_16x16x32_bf16 v[108:111], v[152:155], v[200:203], v[108:111]
	v_mfma_f32_16x16x32_bf16 v[104:107], v[160:163], v[200:203], v[104:107]
	v_mfma_f32_16x16x32_bf16 v[92:95], v[152:155], v[208:211], v[92:95]
	v_mfma_f32_16x16x32_bf16 v[88:91], v[160:163], v[208:211], v[88:91]
	v_mfma_f32_16x16x32_bf16 v[76:79], v[152:155], v[216:219], v[76:79]
	v_mfma_f32_16x16x32_bf16 v[72:75], v[160:163], v[216:219], v[72:75]
	v_mfma_f32_16x16x32_bf16 v[116:119], v[164:167], v[180:183], v[116:119]
	v_mfma_f32_16x16x32_bf16 v[112:115], v[172:175], v[180:183], v[112:115]
	v_mfma_f32_16x16x32_bf16 v[100:103], v[164:167], v[196:199], v[100:103]
	v_mfma_f32_16x16x32_bf16 v[96:99], v[172:175], v[196:199], v[96:99]
	v_mfma_f32_16x16x32_bf16 v[84:87], v[164:167], v[204:207], v[84:87]
	v_mfma_f32_16x16x32_bf16 v[80:83], v[172:175], v[204:207], v[80:83]
	v_mfma_f32_16x16x32_bf16 v[68:71], v[164:167], v[212:215], v[68:71]
	v_mfma_f32_16x16x32_bf16 v[64:67], v[172:175], v[212:215], v[64:67]
	v_mfma_f32_16x16x32_bf16 v[116:119], v[168:171], v[192:195], v[116:119]
	v_mfma_f32_16x16x32_bf16 v[112:115], v[176:179], v[192:195], v[112:115]
	v_mfma_f32_16x16x32_bf16 v[100:103], v[168:171], v[200:203], v[100:103]
	v_mfma_f32_16x16x32_bf16 v[96:99], v[176:179], v[200:203], v[96:99]
	v_mfma_f32_16x16x32_bf16 v[84:87], v[168:171], v[208:211], v[84:87]
	v_mfma_f32_16x16x32_bf16 v[80:83], v[176:179], v[208:211], v[80:83]
	v_mfma_f32_16x16x32_bf16 v[68:71], v[168:171], v[216:219], v[68:71]
	v_mfma_f32_16x16x32_bf16 v[64:67], v[176:179], v[216:219], v[64:67]
	s_barrier
	s_or_b32 s43, s42, 0x80
	v_add_u32_e32 v135, s43, v137
	s_add_i32 s44, s44, s17
	ds_read_b128 v[180:183], v147 offset:49152
	ds_read_b128 v[192:195], v147 offset:50176
	ds_read_b128 v[196:199], v147 offset:51200
	ds_read_b128 v[200:203], v147 offset:52224
	ds_read_b128 v[204:207], v147 offset:53248
	ds_read_b128 v[208:211], v147 offset:54272
	ds_read_b128 v[212:215], v147 offset:55296
	ds_read_b128 v[216:219], v147 offset:56320
	s_mov_b32 m0, s44
	s_add_i32 s42, s42, 0x40080
	global_load_lds_dwordx4 v135, s[10:11]
	v_add_u32_e32 v135, s43, v139
	s_add_i32 m0, s44, 0x2000
	s_add_i32 s43, s45, s17
	global_load_lds_dwordx4 v135, s[10:11]
	v_add_u32_e32 v135, s42, v137
	s_mov_b32 m0, s43
	s_nop 0
	global_load_lds_dwordx4 v135, s[10:11]
	v_add_u32_e32 v135, s42, v139
	s_add_i32 m0, s43, 0x2000
	s_nop 0
	global_load_lds_dwordx4 v135, s[10:11]
	v_add_u32_e32 v135, s41, v136
	s_mov_b32 m0, s26
	s_nop 0
	global_load_lds_dwordx4 v135, s[8:9]
	v_add_u32_e32 v135, s41, v138
	s_mov_b32 m0, s27
	s_nop 0
	global_load_lds_dwordx4 v135, s[8:9]
	s_waitcnt vmcnt(8)
	s_waitcnt lgkmcnt(0)
	s_barrier
	s_waitcnt lgkmcnt(0)
	v_mfma_f32_16x16x32_bf16 v[60:63], v[148:151], v[180:183], v[60:63]
	v_mfma_f32_16x16x32_bf16 v[56:59], v[156:159], v[180:183], v[56:59]
	v_mfma_f32_16x16x32_bf16 v[44:47], v[148:151], v[196:199], v[44:47]
	v_mfma_f32_16x16x32_bf16 v[40:43], v[156:159], v[196:199], v[40:43]
	v_mfma_f32_16x16x32_bf16 v[28:31], v[148:151], v[204:207], v[28:31]
	v_mfma_f32_16x16x32_bf16 v[24:27], v[156:159], v[204:207], v[24:27]
	v_mfma_f32_16x16x32_bf16 v[12:15], v[148:151], v[212:215], v[12:15]
	v_mfma_f32_16x16x32_bf16 v[8:11], v[156:159], v[212:215], v[8:11]
	v_mfma_f32_16x16x32_bf16 v[60:63], v[152:155], v[192:195], v[60:63]
	v_mfma_f32_16x16x32_bf16 v[56:59], v[160:163], v[192:195], v[56:59]
	v_mfma_f32_16x16x32_bf16 v[44:47], v[152:155], v[200:203], v[44:47]
	v_mfma_f32_16x16x32_bf16 v[40:43], v[160:163], v[200:203], v[40:43]
	v_mfma_f32_16x16x32_bf16 v[28:31], v[152:155], v[208:211], v[28:31]
	v_mfma_f32_16x16x32_bf16 v[24:27], v[160:163], v[208:211], v[24:27]
	v_mfma_f32_16x16x32_bf16 v[12:15], v[152:155], v[216:219], v[12:15]
	v_mfma_f32_16x16x32_bf16 v[8:11], v[160:163], v[216:219], v[8:11]
	v_mfma_f32_16x16x32_bf16 v[52:55], v[164:167], v[180:183], v[52:55]
	v_mfma_f32_16x16x32_bf16 v[48:51], v[172:175], v[180:183], v[48:51]
	v_mfma_f32_16x16x32_bf16 v[36:39], v[164:167], v[196:199], v[36:39]
	v_mfma_f32_16x16x32_bf16 v[32:35], v[172:175], v[196:199], v[32:35]
	v_mfma_f32_16x16x32_bf16 v[20:23], v[164:167], v[204:207], v[20:23]
	v_mfma_f32_16x16x32_bf16 v[16:19], v[172:175], v[204:207], v[16:19]
	v_mfma_f32_16x16x32_bf16 v[4:7], v[164:167], v[212:215], v[4:7]
	v_mfma_f32_16x16x32_bf16 v[0:3], v[172:175], v[212:215], v[0:3]
	v_mfma_f32_16x16x32_bf16 v[52:55], v[168:171], v[192:195], v[52:55]
	v_mfma_f32_16x16x32_bf16 v[48:51], v[176:179], v[192:195], v[48:51]
	v_mfma_f32_16x16x32_bf16 v[36:39], v[168:171], v[200:203], v[36:39]
	v_mfma_f32_16x16x32_bf16 v[32:35], v[176:179], v[200:203], v[32:35]
	v_mfma_f32_16x16x32_bf16 v[20:23], v[168:171], v[208:211], v[20:23]
	v_mfma_f32_16x16x32_bf16 v[16:19], v[176:179], v[208:211], v[16:19]
	v_mfma_f32_16x16x32_bf16 v[4:7], v[168:171], v[216:219], v[4:7]
	v_mfma_f32_16x16x32_bf16 v[0:3], v[176:179], v[216:219], v[0:3]
	s_barrier
	s_add_i32 s40, s40, 2
	s_addk_i32 s38, 0x100
	s_addk_i32 s39, 0x100
	v_add_u32_e32 v132, 0x100, v132
	s_cmp_gt_u32 s40, 13
	v_add_u32_e32 v134, 0x100, v134
	s_cbranch_scc1 .Lpeel_done_523
.LBB0_523:
	ds_read_b128 v[148:151], v145
	ds_read_b128 v[152:155], v145 offset:1024
	ds_read_b128 v[156:159], v145 offset:2048
	ds_read_b128 v[160:163], v145 offset:3072
	ds_read_b128 v[164:167], v146
	ds_read_b128 v[168:171], v146 offset:1024
	ds_read_b128 v[172:175], v146 offset:2048
	ds_read_b128 v[176:179], v146 offset:3072
	s_cmp_eq_u32 s40, 12
	s_cselect_b32 s43, s0, s39
	s_cselect_b32 s42, s1, s38
	s_or_b32 s41, s43, 0x80
	v_mov_b32_e32 v135, v134
	ds_read_b128 v[180:183], v147
	ds_read_b128 v[192:195], v147 offset:1024
	ds_read_b128 v[196:199], v147 offset:2048
	ds_read_b128 v[200:203], v147 offset:3072
	ds_read_b128 v[204:207], v147 offset:4096
	ds_read_b128 v[208:211], v147 offset:5120
	ds_read_b128 v[212:215], v147 offset:6144
	ds_read_b128 v[216:219], v147 offset:7168
	s_add_i32 m0, s18, 0xc000
	s_nop 0
	global_load_lds_dwordx4 v135, s[8:9]
	v_mov_b32_e32 v135, v132
	s_add_i32 m0, s18, 0xe000
	s_nop 0
	global_load_lds_dwordx4 v135, s[8:9]
	s_waitcnt vmcnt(8)
	s_waitcnt lgkmcnt(0)
	s_barrier
	s_waitcnt lgkmcnt(0)
	v_mfma_f32_16x16x32_bf16 v[124:127], v[148:151], v[180:183], v[124:127]
	v_mfma_f32_16x16x32_bf16 v[120:123], v[156:159], v[180:183], v[120:123]
	v_mfma_f32_16x16x32_bf16 v[108:111], v[148:151], v[196:199], v[108:111]
	v_mfma_f32_16x16x32_bf16 v[104:107], v[156:159], v[196:199], v[104:107]
	v_mfma_f32_16x16x32_bf16 v[92:95], v[148:151], v[204:207], v[92:95]
	v_mfma_f32_16x16x32_bf16 v[88:91], v[156:159], v[204:207], v[88:91]
	v_mfma_f32_16x16x32_bf16 v[76:79], v[148:151], v[212:215], v[76:79]
	v_mfma_f32_16x16x32_bf16 v[72:75], v[156:159], v[212:215], v[72:75]
	v_mfma_f32_16x16x32_bf16 v[124:127], v[152:155], v[192:195], v[124:127]
	v_mfma_f32_16x16x32_bf16 v[120:123], v[160:163], v[192:195], v[120:123]
	v_mfma_f32_16x16x32_bf16 v[108:111], v[152:155], v[200:203], v[108:111]
	v_mfma_f32_16x16x32_bf16 v[104:107], v[160:163], v[200:203], v[104:107]
	v_mfma_f32_16x16x32_bf16 v[92:95], v[152:155], v[208:211], v[92:95]
	v_mfma_f32_16x16x32_bf16 v[88:91], v[160:163], v[208:211], v[88:91]
	v_mfma_f32_16x16x32_bf16 v[76:79], v[152:155], v[216:219], v[76:79]
	v_mfma_f32_16x16x32_bf16 v[72:75], v[160:163], v[216:219], v[72:75]
	v_mfma_f32_16x16x32_bf16 v[116:119], v[164:167], v[180:183], v[116:119]
	v_mfma_f32_16x16x32_bf16 v[112:115], v[172:175], v[180:183], v[112:115]
	v_mfma_f32_16x16x32_bf16 v[100:103], v[164:167], v[196:199], v[100:103]
	v_mfma_f32_16x16x32_bf16 v[96:99], v[172:175], v[196:199], v[96:99]
	v_mfma_f32_16x16x32_bf16 v[84:87], v[164:167], v[204:207], v[84:87]
	v_mfma_f32_16x16x32_bf16 v[80:83], v[172:175], v[204:207], v[80:83]
	v_mfma_f32_16x16x32_bf16 v[68:71], v[164:167], v[212:215], v[68:71]
	v_mfma_f32_16x16x32_bf16 v[64:67], v[172:175], v[212:215], v[64:67]
	v_mfma_f32_16x16x32_bf16 v[116:119], v[168:171], v[192:195], v[116:119]
	v_mfma_f32_16x16x32_bf16 v[112:115], v[176:179], v[192:195], v[112:115]
	v_mfma_f32_16x16x32_bf16 v[100:103], v[168:171], v[200:203], v[100:103]
	v_mfma_f32_16x16x32_bf16 v[96:99], v[176:179], v[200:203], v[96:99]
	v_mfma_f32_16x16x32_bf16 v[84:87], v[168:171], v[208:211], v[84:87]
	v_mfma_f32_16x16x32_bf16 v[80:83], v[176:179], v[208:211], v[80:83]
	v_mfma_f32_16x16x32_bf16 v[68:71], v[168:171], v[216:219], v[68:71]
	v_mfma_f32_16x16x32_bf16 v[64:67], v[176:179], v[216:219], v[64:67]
	s_barrier
	v_add_u32_e32 v135, s42, v137
	s_add_i32 s44, s30, s17
	ds_read_b128 v[180:183], v147 offset:16384
	ds_read_b128 v[192:195], v147 offset:17408
	ds_read_b128 v[196:199], v147 offset:18432
	ds_read_b128 v[200:203], v147 offset:19456
	ds_read_b128 v[204:207], v147 offset:20480
	ds_read_b128 v[208:211], v147 offset:21504
	ds_read_b128 v[212:215], v147 offset:22528
	ds_read_b128 v[216:219], v147 offset:23552
	s_mov_b32 m0, s44
	s_add_i32 s45, s31, s17
	global_load_lds_dwordx4 v135, s[10:11]
	v_add_u32_e32 v135, s42, v139
	s_add_i32 m0, s44, 0x2000
	s_add_i32 s44, s42, 0x40000
	global_load_lds_dwordx4 v135, s[10:11]
	v_add_u32_e32 v135, s44, v137
	s_mov_b32 m0, s45
	s_nop 0
	global_load_lds_dwordx4 v135, s[10:11]
	v_add_u32_e32 v135, s44, v139
	s_add_i32 m0, s45, 0x2000
	s_nop 0
	global_load_lds_dwordx4 v135, s[10:11]
	v_add_u32_e32 v135, s43, v136
	s_mov_b32 m0, s18
	s_nop 0
	global_load_lds_dwordx4 v135, s[8:9]
	v_add_u32_e32 v135, s43, v138
	s_mov_b32 m0, s19
	s_nop 0
	global_load_lds_dwordx4 v135, s[8:9]
	s_waitcnt vmcnt(8)
	s_waitcnt lgkmcnt(0)
	s_barrier
	s_waitcnt lgkmcnt(0)
	v_mfma_f32_16x16x32_bf16 v[60:63], v[148:151], v[180:183], v[60:63]
	v_mfma_f32_16x16x32_bf16 v[56:59], v[156:159], v[180:183], v[56:59]
	v_mfma_f32_16x16x32_bf16 v[44:47], v[148:151], v[196:199], v[44:47]
	v_mfma_f32_16x16x32_bf16 v[40:43], v[156:159], v[196:199], v[40:43]
	v_mfma_f32_16x16x32_bf16 v[28:31], v[148:151], v[204:207], v[28:31]
	v_mfma_f32_16x16x32_bf16 v[24:27], v[156:159], v[204:207], v[24:27]
	v_mfma_f32_16x16x32_bf16 v[12:15], v[148:151], v[212:215], v[12:15]
	v_mfma_f32_16x16x32_bf16 v[8:11], v[156:159], v[212:215], v[8:11]
	v_mfma_f32_16x16x32_bf16 v[60:63], v[152:155], v[192:195], v[60:63]
	v_mfma_f32_16x16x32_bf16 v[56:59], v[160:163], v[192:195], v[56:59]
	v_mfma_f32_16x16x32_bf16 v[44:47], v[152:155], v[200:203], v[44:47]
	v_mfma_f32_16x16x32_bf16 v[40:43], v[160:163], v[200:203], v[40:43]
	v_mfma_f32_16x16x32_bf16 v[28:31], v[152:155], v[208:211], v[28:31]
	v_mfma_f32_16x16x32_bf16 v[24:27], v[160:163], v[208:211], v[24:27]
	v_mfma_f32_16x16x32_bf16 v[12:15], v[152:155], v[216:219], v[12:15]
	v_mfma_f32_16x16x32_bf16 v[8:11], v[160:163], v[216:219], v[8:11]
	v_mfma_f32_16x16x32_bf16 v[52:55], v[164:167], v[180:183], v[52:55]
	v_mfma_f32_16x16x32_bf16 v[48:51], v[172:175], v[180:183], v[48:51]
	v_mfma_f32_16x16x32_bf16 v[36:39], v[164:167], v[196:199], v[36:39]
	v_mfma_f32_16x16x32_bf16 v[32:35], v[172:175], v[196:199], v[32:35]
	v_mfma_f32_16x16x32_bf16 v[20:23], v[164:167], v[204:207], v[20:23]
	v_mfma_f32_16x16x32_bf16 v[16:19], v[172:175], v[204:207], v[16:19]
	v_mfma_f32_16x16x32_bf16 v[4:7], v[164:167], v[212:215], v[4:7]
	v_mfma_f32_16x16x32_bf16 v[0:3], v[172:175], v[212:215], v[0:3]
	v_mfma_f32_16x16x32_bf16 v[52:55], v[168:171], v[192:195], v[52:55]
	v_mfma_f32_16x16x32_bf16 v[48:51], v[176:179], v[192:195], v[48:51]
	v_mfma_f32_16x16x32_bf16 v[36:39], v[168:171], v[200:203], v[36:39]
	v_mfma_f32_16x16x32_bf16 v[32:35], v[176:179], v[200:203], v[32:35]
	v_mfma_f32_16x16x32_bf16 v[20:23], v[168:171], v[208:211], v[20:23]
	v_mfma_f32_16x16x32_bf16 v[16:19], v[176:179], v[208:211], v[16:19]
	v_mfma_f32_16x16x32_bf16 v[4:7], v[168:171], v[216:219], v[4:7]
	v_mfma_f32_16x16x32_bf16 v[0:3], v[176:179], v[216:219], v[0:3]
	s_barrier
; #define PG8_BAR __builtin_amdgcn_s_barrier()
;     ...
;         if constexpr (Epi::MIDHOOK) {
;             for (int t = 0; t < 4; t += 2) PG8_ITER(t);
;             E.mid(acc, cur, wr, wc, fr, fq);
;             for (int t = 4; t < nt; t += 2) PG8_ITER(t);
;         } else {
;             for (int t = 0; t < nt; t += 2) PG8_ITER(t);
;         }
;     ...
;         if constexpr (ALIGN_EPI) { if (wr == 0) PG8_BAR; }
	s_add_i32 s44, 0, 0x18000
	v_add_u32_e32 v135, s44, v141
	s_add_i32 s45, 0, 0x1c000
	ds_read_b128 v[148:151], v135
	ds_read_b128 v[152:155], v135 offset:1024
	ds_read_b128 v[156:159], v135 offset:2048
	ds_read_b128 v[160:163], v135 offset:3072
	v_add_u32_e32 v135, s45, v141
	ds_read_b128 v[164:167], v135
	ds_read_b128 v[168:171], v135 offset:1024
	ds_read_b128 v[172:175], v135 offset:2048
	ds_read_b128 v[176:179], v135 offset:3072
	s_add_i32 s43, s43, 0x40000
	v_add_u32_e32 v135, s43, v136
	s_mov_b32 m0, s20
	ds_read_b128 v[180:183], v147 offset:32768
	ds_read_b128 v[192:195], v147 offset:33792
	ds_read_b128 v[196:199], v147 offset:34816
	ds_read_b128 v[200:203], v147 offset:35840
	ds_read_b128 v[204:207], v147 offset:36864
	ds_read_b128 v[208:211], v147 offset:37888
	ds_read_b128 v[212:215], v147 offset:38912
	ds_read_b128 v[216:219], v147 offset:39936
	s_nop 0
	global_load_lds_dwordx4 v135, s[8:9]
	v_add_u32_e32 v135, s43, v138
	s_mov_b32 m0, s21
	s_nop 0
	global_load_lds_dwordx4 v135, s[8:9]
	s_waitcnt vmcnt(8)
	s_waitcnt lgkmcnt(0)
	s_barrier
	s_waitcnt lgkmcnt(0)
	v_mfma_f32_16x16x32_bf16 v[124:127], v[148:151], v[180:183], v[124:127]
	v_mfma_f32_16x16x32_bf16 v[120:123], v[156:159], v[180:183], v[120:123]
	v_mfma_f32_16x16x32_bf16 v[108:111], v[148:151], v[196:199], v[108:111]
	v_mfma_f32_16x16x32_bf16 v[104:107], v[156:159], v[196:199], v[104:107]
	v_mfma_f32_16x16x32_bf16 v[92:95], v[148:151], v[204:207], v[92:95]
	v_mfma_f32_16x16x32_bf16 v[88:91], v[156:159], v[204:207], v[88:91]
	v_mfma_f32_16x16x32_bf16 v[76:79], v[148:151], v[212:215], v[76:79]
	v_mfma_f32_16x16x32_bf16 v[72:75], v[156:159], v[212:215], v[72:75]
	v_mfma_f32_16x16x32_bf16 v[124:127], v[152:155], v[192:195], v[124:127]
	v_mfma_f32_16x16x32_bf16 v[120:123], v[160:163], v[192:195], v[120:123]
	v_mfma_f32_16x16x32_bf16 v[108:111], v[152:155], v[200:203], v[108:111]
	v_mfma_f32_16x16x32_bf16 v[104:107], v[160:163], v[200:203], v[104:107]
	v_mfma_f32_16x16x32_bf16 v[92:95], v[152:155], v[208:211], v[92:95]
	v_mfma_f32_16x16x32_bf16 v[88:91], v[160:163], v[208:211], v[88:91]
	v_mfma_f32_16x16x32_bf16 v[76:79], v[152:155], v[216:219], v[76:79]
	v_mfma_f32_16x16x32_bf16 v[72:75], v[160:163], v[216:219], v[72:75]
	v_mfma_f32_16x16x32_bf16 v[116:119], v[164:167], v[180:183], v[116:119]
	v_mfma_f32_16x16x32_bf16 v[112:115], v[172:175], v[180:183], v[112:115]
	v_mfma_f32_16x16x32_bf16 v[100:103], v[164:167], v[196:199], v[100:103]
	v_mfma_f32_16x16x32_bf16 v[96:99], v[172:175], v[196:199], v[96:99]
	v_mfma_f32_16x16x32_bf16 v[84:87], v[164:167], v[204:207], v[84:87]
	v_mfma_f32_16x16x32_bf16 v[80:83], v[172:175], v[204:207], v[80:83]
	v_mfma_f32_16x16x32_bf16 v[68:71], v[164:167], v[212:215], v[68:71]
	v_mfma_f32_16x16x32_bf16 v[64:67], v[172:175], v[212:215], v[64:67]
	v_mfma_f32_16x16x32_bf16 v[116:119], v[168:171], v[192:195], v[116:119]
	v_mfma_f32_16x16x32_bf16 v[112:115], v[176:179], v[192:195], v[112:115]
	v_mfma_f32_16x16x32_bf16 v[100:103], v[168:171], v[200:203], v[100:103]
	v_mfma_f32_16x16x32_bf16 v[96:99], v[176:179], v[200:203], v[96:99]
	v_mfma_f32_16x16x32_bf16 v[84:87], v[168:171], v[208:211], v[84:87]
	v_mfma_f32_16x16x32_bf16 v[80:83], v[176:179], v[208:211], v[80:83]
	v_mfma_f32_16x16x32_bf16 v[68:71], v[168:171], v[216:219], v[68:71]
	v_mfma_f32_16x16x32_bf16 v[64:67], v[176:179], v[216:219], v[64:67]
	s_barrier
	s_or_b32 s43, s42, 0x80
	v_add_u32_e32 v135, s43, v137
	s_add_i32 s44, s44, s17
	ds_read_b128 v[180:183], v147 offset:49152
	ds_read_b128 v[192:195], v147 offset:50176
	ds_read_b128 v[196:199], v147 offset:51200
	ds_read_b128 v[200:203], v147 offset:52224
	ds_read_b128 v[204:207], v147 offset:53248
	ds_read_b128 v[208:211], v147 offset:54272
	ds_read_b128 v[212:215], v147 offset:55296
	ds_read_b128 v[216:219], v147 offset:56320
	s_mov_b32 m0, s44
	s_add_i32 s42, s42, 0x40080
	global_load_lds_dwordx4 v135, s[10:11]
	v_add_u32_e32 v135, s43, v139
	s_add_i32 m0, s44, 0x2000
	s_add_i32 s43, s45, s17
	global_load_lds_dwordx4 v135, s[10:11]
	v_add_u32_e32 v135, s42, v137
	s_mov_b32 m0, s43
	s_nop 0
	global_load_lds_dwordx4 v135, s[10:11]
	v_add_u32_e32 v135, s42, v139
	s_add_i32 m0, s43, 0x2000
	s_nop 0
	global_load_lds_dwordx4 v135, s[10:11]
	v_add_u32_e32 v135, s41, v136
	s_mov_b32 m0, s26
	s_nop 0
	global_load_lds_dwordx4 v135, s[8:9]
	v_add_u32_e32 v135, s41, v138
	s_mov_b32 m0, s27
	s_nop 0
	global_load_lds_dwordx4 v135, s[8:9]
	s_waitcnt vmcnt(8)
	s_waitcnt lgkmcnt(0)
	s_barrier
	s_waitcnt lgkmcnt(0)
	v_mfma_f32_16x16x32_bf16 v[60:63], v[148:151], v[180:183], v[60:63]
	v_mfma_f32_16x16x32_bf16 v[56:59], v[156:159], v[180:183], v[56:59]
	v_mfma_f32_16x16x32_bf16 v[44:47], v[148:151], v[196:199], v[44:47]
	v_mfma_f32_16x16x32_bf16 v[40:43], v[156:159], v[196:199], v[40:43]
	v_mfma_f32_16x16x32_bf16 v[28:31], v[148:151], v[204:207], v[28:31]
	v_mfma_f32_16x16x32_bf16 v[24:27], v[156:159], v[204:207], v[24:27]
	v_mfma_f32_16x16x32_bf16 v[12:15], v[148:151], v[212:215], v[12:15]
	v_mfma_f32_16x16x32_bf16 v[8:11], v[156:159], v[212:215], v[8:11]
	v_mfma_f32_16x16x32_bf16 v[60:63], v[152:155], v[192:195], v[60:63]
	v_mfma_f32_16x16x32_bf16 v[56:59], v[160:163], v[192:195], v[56:59]
	v_mfma_f32_16x16x32_bf16 v[44:47], v[152:155], v[200:203], v[44:47]
	v_mfma_f32_16x16x32_bf16 v[40:43], v[160:163], v[200:203], v[40:43]
	v_mfma_f32_16x16x32_bf16 v[28:31], v[152:155], v[208:211], v[28:31]
	v_mfma_f32_16x16x32_bf16 v[24:27], v[160:163], v[208:211], v[24:27]
	v_mfma_f32_16x16x32_bf16 v[12:15], v[152:155], v[216:219], v[12:15]
	v_mfma_f32_16x16x32_bf16 v[8:11], v[160:163], v[216:219], v[8:11]
	v_mfma_f32_16x16x32_bf16 v[52:55], v[164:167], v[180:183], v[52:55]
	v_mfma_f32_16x16x32_bf16 v[48:51], v[172:175], v[180:183], v[48:51]
	v_mfma_f32_16x16x32_bf16 v[36:39], v[164:167], v[196:199], v[36:39]
	v_mfma_f32_16x16x32_bf16 v[32:35], v[172:175], v[196:199], v[32:35]
	v_mfma_f32_16x16x32_bf16 v[20:23], v[164:167], v[204:207], v[20:23]
	v_mfma_f32_16x16x32_bf16 v[16:19], v[172:175], v[204:207], v[16:19]
	v_mfma_f32_16x16x32_bf16 v[4:7], v[164:167], v[212:215], v[4:7]
	v_mfma_f32_16x16x32_bf16 v[0:3], v[172:175], v[212:215], v[0:3]
	v_mfma_f32_16x16x32_bf16 v[52:55], v[168:171], v[192:195], v[52:55]
	v_mfma_f32_16x16x32_bf16 v[48:51], v[176:179], v[192:195], v[48:51]
	v_mfma_f32_16x16x32_bf16 v[36:39], v[168:171], v[200:203], v[36:39]
	v_mfma_f32_16x16x32_bf16 v[32:35], v[176:179], v[200:203], v[32:35]
	v_mfma_f32_16x16x32_bf16 v[20:23], v[168:171], v[208:211], v[20:23]
	v_mfma_f32_16x16x32_bf16 v[16:19], v[176:179], v[208:211], v[16:19]
	v_mfma_f32_16x16x32_bf16 v[4:7], v[168:171], v[216:219], v[4:7]
	v_mfma_f32_16x16x32_bf16 v[0:3], v[176:179], v[216:219], v[0:3]
	s_barrier
	s_add_i32 s40, s40, 2
	s_addk_i32 s38, 0x100
	s_addk_i32 s39, 0x100
	v_add_u32_e32 v132, 0x100, v132
	s_cmp_gt_u32 s40, 13
	v_add_u32_e32 v134, 0x100, v134
	s_cbranch_scc0 .LBB0_523
.Lpeel_done_523:
	s_and_b64 vcc, exec, s[14:15]
	s_cbranch_vccz .LBB0_526
	s_barrier

;     ...
;         const bool has_next = S.next(ui + 1, nxt);
;         const unsigned nA = has_next ? (unsigned)nxt.pm * tstepA : cA, nB = has_next ? (unsigned)nxt.pn * tstepB : cB;
.LBB0_779:
	s_mul_i32 s76, s75, 0x7e000
	s_and_b64 s[0:1], s[8:9], exec
	s_cselect_b32 s0, s76, s2
	s_lshl_b32 s77, s74, 19
	s_and_b64 s[12:13], s[8:9], exec
	v_mov_b32_e32 v12, 0
	s_cselect_b32 s1, s77, s3
	s_addk_i32 s2, 0x2080
	s_addk_i32 s3, 0x100
	s_mov_b32 s11, -2
	s_waitcnt vmcnt(0)
	ds_read_b128 v[128:131], v207
	ds_read_b128 v[132:135], v207 offset:1024
	ds_read_b128 v[136:139], v207 offset:2048
	ds_read_b128 v[140:143], v207 offset:3072
	ds_read_b128 v[144:147], v208
	ds_read_b128 v[148:151], v208 offset:1024
	ds_read_b128 v[152:155], v208 offset:2048
	ds_read_b128 v[156:159], v208 offset:3072
	s_add_i32 s12, s2, 0xffffe080
	s_cmp_eq_u32 s11, 12
	s_cselect_b32 s14, s0, s12
	s_cselect_b32 s13, s1, s3
	s_or_b32 s12, s14, 0x80
	v_add_u32_e32 v184, s2, v206
	ds_read_b128 v[164:167], v209
	ds_read_b128 v[168:171], v209 offset:1024
	ds_read_b128 v[172:175], v209 offset:2048
	ds_read_b128 v[176:179], v209 offset:3072
	ds_read_b128 v[180:183], v209 offset:4096
	ds_read_b128 v[210:213], v209 offset:5120
	ds_read_b128 v[214:217], v209 offset:6144
	ds_read_b128 v[218:221], v209 offset:7168
	s_add_i32 m0, s27, 0xc000
	s_nop 0
	global_load_lds_dwordx4 v184, s[22:23]
	v_add_u32_e32 v184, s2, v205
	s_add_i32 m0, s27, 0xe000
	s_nop 0
	global_load_lds_dwordx4 v184, s[22:23]
	s_waitcnt vmcnt(8)
	s_waitcnt lgkmcnt(0)
	s_barrier
	s_waitcnt lgkmcnt(0)
	v_mfma_f32_16x16x32_bf16 v[120:123], v[128:131], v[164:167], 0
	v_mfma_f32_16x16x32_bf16 v[56:59], v[136:139], v[164:167], 0
	v_mfma_f32_16x16x32_bf16 v[112:115], v[128:131], v[172:175], 0
	v_mfma_f32_16x16x32_bf16 v[48:51], v[136:139], v[172:175], 0
	v_mfma_f32_16x16x32_bf16 v[104:107], v[128:131], v[180:183], 0
	v_mfma_f32_16x16x32_bf16 v[40:43], v[136:139], v[180:183], 0
	v_mfma_f32_16x16x32_bf16 v[96:99], v[128:131], v[214:217], 0
	v_mfma_f32_16x16x32_bf16 v[32:35], v[136:139], v[214:217], 0
	v_mfma_f32_16x16x32_bf16 v[120:123], v[132:135], v[168:171], v[120:123]
	v_mfma_f32_16x16x32_bf16 v[56:59], v[140:143], v[168:171], v[56:59]
	v_mfma_f32_16x16x32_bf16 v[112:115], v[132:135], v[176:179], v[112:115]
	v_mfma_f32_16x16x32_bf16 v[48:51], v[140:143], v[176:179], v[48:51]
	v_mfma_f32_16x16x32_bf16 v[104:107], v[132:135], v[210:213], v[104:107]
	v_mfma_f32_16x16x32_bf16 v[40:43], v[140:143], v[210:213], v[40:43]
	v_mfma_f32_16x16x32_bf16 v[96:99], v[132:135], v[218:221], v[96:99]
	v_mfma_f32_16x16x32_bf16 v[32:35], v[140:143], v[218:221], v[32:35]
	v_mfma_f32_16x16x32_bf16 v[124:127], v[144:147], v[164:167], 0
	v_mfma_f32_16x16x32_bf16 v[60:63], v[152:155], v[164:167], 0
	v_mfma_f32_16x16x32_bf16 v[116:119], v[144:147], v[172:175], 0
	v_mfma_f32_16x16x32_bf16 v[52:55], v[152:155], v[172:175], 0
	v_mfma_f32_16x16x32_bf16 v[108:111], v[144:147], v[180:183], 0
	v_mfma_f32_16x16x32_bf16 v[44:47], v[152:155], v[180:183], 0
	v_mfma_f32_16x16x32_bf16 v[100:103], v[144:147], v[214:217], 0
	v_mfma_f32_16x16x32_bf16 v[36:39], v[152:155], v[214:217], 0
	v_mfma_f32_16x16x32_bf16 v[124:127], v[148:151], v[168:171], v[124:127]
	v_mfma_f32_16x16x32_bf16 v[60:63], v[156:159], v[168:171], v[60:63]
	v_mfma_f32_16x16x32_bf16 v[116:119], v[148:151], v[176:179], v[116:119]
	v_mfma_f32_16x16x32_bf16 v[52:55], v[156:159], v[176:179], v[52:55]
	v_mfma_f32_16x16x32_bf16 v[108:111], v[148:151], v[210:213], v[108:111]
	v_mfma_f32_16x16x32_bf16 v[44:47], v[156:159], v[210:213], v[44:47]
	v_mfma_f32_16x16x32_bf16 v[100:103], v[148:151], v[218:221], v[100:103]
	v_mfma_f32_16x16x32_bf16 v[36:39], v[156:159], v[218:221], v[36:39]
	s_barrier
	v_add_u32_e32 v184, s13, v192
	s_add_i32 s15, s71, s26
	ds_read_b128 v[164:167], v209 offset:16384
	ds_read_b128 v[168:171], v209 offset:17408
	ds_read_b128 v[172:175], v209 offset:18432
	ds_read_b128 v[176:179], v209 offset:19456
	ds_read_b128 v[180:183], v209 offset:20480
	ds_read_b128 v[210:213], v209 offset:21504
	ds_read_b128 v[214:217], v209 offset:22528
	ds_read_b128 v[218:221], v209 offset:23552
	s_mov_b32 m0, s15
	s_add_i32 s16, s72, s26
	global_load_lds_dwordx4 v184, s[36:37]
	v_add_u32_e32 v184, s13, v194
	s_add_i32 m0, s15, 0x2000
	s_add_i32 s15, s13, 0x40000
	global_load_lds_dwordx4 v184, s[36:37]
	v_add_u32_e32 v184, s15, v192
	s_mov_b32 m0, s16
	s_nop 0
	global_load_lds_dwordx4 v184, s[36:37]
	v_add_u32_e32 v184, s15, v194
	s_add_i32 m0, s16, 0x2000
	s_nop 0
	global_load_lds_dwordx4 v184, s[36:37]
	v_add_u32_e32 v184, s14, v191
	s_mov_b32 m0, s27
	s_nop 0
	global_load_lds_dwordx4 v184, s[22:23]
	v_add_u32_e32 v184, s14, v193
	s_mov_b32 m0, s33
	s_nop 0
	global_load_lds_dwordx4 v184, s[22:23]
	s_waitcnt vmcnt(8)
	s_waitcnt lgkmcnt(0)
	s_barrier
	s_waitcnt lgkmcnt(0)
	v_mfma_f32_16x16x32_bf16 v[88:91], v[128:131], v[164:167], 0
	v_mfma_f32_16x16x32_bf16 v[24:27], v[136:139], v[164:167], 0
	v_mfma_f32_16x16x32_bf16 v[72:75], v[128:131], v[172:175], 0
	v_mfma_f32_16x16x32_bf16 v[8:11], v[136:139], v[172:175], 0
	v_mfma_f32_16x16x32_bf16 v[68:71], v[128:131], v[180:183], 0
	v_mfma_f32_16x16x32_bf16 v[4:7], v[136:139], v[180:183], 0
	v_mfma_f32_16x16x32_bf16 v[64:67], v[128:131], v[214:217], 0
	v_mfma_f32_16x16x32_bf16 v[0:3], v[136:139], v[214:217], 0
	v_mfma_f32_16x16x32_bf16 v[88:91], v[132:135], v[168:171], v[88:91]
	v_mfma_f32_16x16x32_bf16 v[24:27], v[140:143], v[168:171], v[24:27]
	v_mfma_f32_16x16x32_bf16 v[72:75], v[132:135], v[176:179], v[72:75]
	v_mfma_f32_16x16x32_bf16 v[8:11], v[140:143], v[176:179], v[8:11]
	v_mfma_f32_16x16x32_bf16 v[68:71], v[132:135], v[210:213], v[68:71]
	v_mfma_f32_16x16x32_bf16 v[4:7], v[140:143], v[210:213], v[4:7]
	v_mfma_f32_16x16x32_bf16 v[64:67], v[132:135], v[218:221], v[64:67]
	v_mfma_f32_16x16x32_bf16 v[0:3], v[140:143], v[218:221], v[0:3]
	v_mfma_f32_16x16x32_bf16 v[92:95], v[144:147], v[164:167], 0
	v_mfma_f32_16x16x32_bf16 v[28:31], v[152:155], v[164:167], 0
	v_mfma_f32_16x16x32_bf16 v[76:79], v[144:147], v[172:175], 0
	v_mfma_f32_16x16x32_bf16 v[16:19], v[152:155], v[172:175], 0
	v_mfma_f32_16x16x32_bf16 v[84:87], v[144:147], v[180:183], 0
	v_mfma_f32_16x16x32_bf16 v[20:23], v[152:155], v[180:183], 0
	v_mfma_f32_16x16x32_bf16 v[80:83], v[144:147], v[214:217], 0
	v_mfma_f32_16x16x32_bf16 v[12:15], v[152:155], v[214:217], 0
	v_mfma_f32_16x16x32_bf16 v[92:95], v[148:151], v[168:171], v[92:95]
	v_mfma_f32_16x16x32_bf16 v[28:31], v[156:159], v[168:171], v[28:31]
	v_mfma_f32_16x16x32_bf16 v[76:79], v[148:151], v[176:179], v[76:79]
	v_mfma_f32_16x16x32_bf16 v[16:19], v[156:159], v[176:179], v[16:19]
	v_mfma_f32_16x16x32_bf16 v[84:87], v[148:151], v[210:213], v[84:87]
	v_mfma_f32_16x16x32_bf16 v[20:23], v[156:159], v[210:213], v[20:23]
	v_mfma_f32_16x16x32_bf16 v[80:83], v[148:151], v[218:221], v[80:83]
	v_mfma_f32_16x16x32_bf16 v[12:15], v[156:159], v[218:221], v[12:15]
	s_barrier
	s_add_i32 s15, 0, 0x18000
	s_add_i32 s16, 0, 0x1c000
	v_add_u32_e32 v140, s15, v195
	v_add_u32_e32 v156, s16, v195
	ds_read_b128 v[128:131], v140
	ds_read_b128 v[132:135], v140 offset:1024
	ds_read_b128 v[136:139], v140 offset:2048
	ds_read_b128 v[140:143], v140 offset:3072
	ds_read_b128 v[144:147], v156
	ds_read_b128 v[148:151], v156 offset:1024
	ds_read_b128 v[152:155], v156 offset:2048
	ds_read_b128 v[156:159], v156 offset:3072
	s_addk_i32 s14, 0x2000
	v_add_u32_e32 v184, s14, v191
	s_mov_b32 m0, s34
	ds_read_b128 v[164:167], v209 offset:32768
	ds_read_b128 v[168:171], v209 offset:33792
	ds_read_b128 v[172:175], v209 offset:34816
	ds_read_b128 v[176:179], v209 offset:35840
	ds_read_b128 v[180:183], v209 offset:36864
	ds_read_b128 v[210:213], v209 offset:37888
	ds_read_b128 v[214:217], v209 offset:38912
	ds_read_b128 v[218:221], v209 offset:39936
	s_nop 0
	global_load_lds_dwordx4 v184, s[22:23]
	v_add_u32_e32 v184, s14, v193
	s_mov_b32 m0, s35
	s_nop 0
	global_load_lds_dwordx4 v184, s[22:23]
	s_waitcnt vmcnt(8)
	s_waitcnt lgkmcnt(0)
	s_barrier
	s_waitcnt lgkmcnt(0)
	v_mfma_f32_16x16x32_bf16 v[120:123], v[128:131], v[164:167], v[120:123]
	v_mfma_f32_16x16x32_bf16 v[56:59], v[136:139], v[164:167], v[56:59]
	v_mfma_f32_16x16x32_bf16 v[112:115], v[128:131], v[172:175], v[112:115]
	v_mfma_f32_16x16x32_bf16 v[48:51], v[136:139], v[172:175], v[48:51]
	v_mfma_f32_16x16x32_bf16 v[104:107], v[128:131], v[180:183], v[104:107]
	v_mfma_f32_16x16x32_bf16 v[40:43], v[136:139], v[180:183], v[40:43]
	v_mfma_f32_16x16x32_bf16 v[96:99], v[128:131], v[214:217], v[96:99]
	v_mfma_f32_16x16x32_bf16 v[32:35], v[136:139], v[214:217], v[32:35]
	v_mfma_f32_16x16x32_bf16 v[120:123], v[132:135], v[168:171], v[120:123]
	v_mfma_f32_16x16x32_bf16 v[56:59], v[140:143], v[168:171], v[56:59]
	v_mfma_f32_16x16x32_bf16 v[112:115], v[132:135], v[176:179], v[112:115]
	v_mfma_f32_16x16x32_bf16 v[48:51], v[140:143], v[176:179], v[48:51]
	v_mfma_f32_16x16x32_bf16 v[104:107], v[132:135], v[210:213], v[104:107]
	v_mfma_f32_16x16x32_bf16 v[40:43], v[140:143], v[210:213], v[40:43]
	v_mfma_f32_16x16x32_bf16 v[96:99], v[132:135], v[218:221], v[96:99]
	v_mfma_f32_16x16x32_bf16 v[32:35], v[140:143], v[218:221], v[32:35]
	v_mfma_f32_16x16x32_bf16 v[124:127], v[144:147], v[164:167], v[124:127]
	v_mfma_f32_16x16x32_bf16 v[60:63], v[152:155], v[164:167], v[60:63]
	v_mfma_f32_16x16x32_bf16 v[116:119], v[144:147], v[172:175], v[116:119]
	v_mfma_f32_16x16x32_bf16 v[52:55], v[152:155], v[172:175], v[52:55]
	v_mfma_f32_16x16x32_bf16 v[108:111], v[144:147], v[180:183], v[108:111]
	v_mfma_f32_16x16x32_bf16 v[44:47], v[152:155], v[180:183], v[44:47]
	v_mfma_f32_16x16x32_bf16 v[100:103], v[144:147], v[214:217], v[100:103]
	v_mfma_f32_16x16x32_bf16 v[36:39], v[152:155], v[214:217], v[36:39]
	v_mfma_f32_16x16x32_bf16 v[124:127], v[148:151], v[168:171], v[124:127]
	v_mfma_f32_16x16x32_bf16 v[60:63], v[156:159], v[168:171], v[60:63]
	v_mfma_f32_16x16x32_bf16 v[116:119], v[148:151], v[176:179], v[116:119]
	v_mfma_f32_16x16x32_bf16 v[52:55], v[156:159], v[176:179], v[52:55]
	v_mfma_f32_16x16x32_bf16 v[108:111], v[148:151], v[210:213], v[108:111]
	v_mfma_f32_16x16x32_bf16 v[44:47], v[156:159], v[210:213], v[44:47]
	v_mfma_f32_16x16x32_bf16 v[100:103], v[148:151], v[218:221], v[100:103]
	v_mfma_f32_16x16x32_bf16 v[36:39], v[156:159], v[218:221], v[36:39]
	s_barrier
;     ...
;         if constexpr (Epi::MIDHOOK) {
;             for (int t = 0; t < 4; t += 2) PG8_ITER(t);
;             E.mid(acc, cur, wr, wc, fr, fq);
;             for (int t = 4; t < nt; t += 2) PG8_ITER(t);
;         } else {
;             for (int t = 0; t < nt; t += 2) PG8_ITER(t);
	s_or_b32 s14, s13, 0x80
	v_add_u32_e32 v184, s14, v192
	s_add_i32 s15, s15, s26
	ds_read_b128 v[164:167], v209 offset:49152
	ds_read_b128 v[168:171], v209 offset:50176
	ds_read_b128 v[172:175], v209 offset:51200
	ds_read_b128 v[176:179], v209 offset:52224
	ds_read_b128 v[180:183], v209 offset:53248
	ds_read_b128 v[210:213], v209 offset:54272
	ds_read_b128 v[214:217], v209 offset:55296
	ds_read_b128 v[218:221], v209 offset:56320
	s_mov_b32 m0, s15
	s_add_i32 s13, s13, 0x40080
	global_load_lds_dwordx4 v184, s[36:37]
	v_add_u32_e32 v184, s14, v194
	s_add_i32 m0, s15, 0x2000
	s_add_i32 s14, s16, s26
	global_load_lds_dwordx4 v184, s[36:37]
	v_add_u32_e32 v184, s13, v192
	s_mov_b32 m0, s14
	s_nop 0
	global_load_lds_dwordx4 v184, s[36:37]
	v_add_u32_e32 v184, s13, v194
	s_add_i32 m0, s14, 0x2000
	s_nop 0
	global_load_lds_dwordx4 v184, s[36:37]
	v_add_u32_e32 v184, s12, v191
	s_mov_b32 m0, s61
	s_nop 0
	global_load_lds_dwordx4 v184, s[22:23]
	v_add_u32_e32 v184, s12, v193
	s_mov_b32 m0, s63
	s_nop 0
	global_load_lds_dwordx4 v184, s[22:23]
	s_waitcnt vmcnt(8)
	s_waitcnt lgkmcnt(0)
	s_barrier
	s_waitcnt lgkmcnt(0)
	v_mfma_f32_16x16x32_bf16 v[88:91], v[128:131], v[164:167], v[88:91]
	v_mfma_f32_16x16x32_bf16 v[24:27], v[136:139], v[164:167], v[24:27]
	v_mfma_f32_16x16x32_bf16 v[72:75], v[128:131], v[172:175], v[72:75]
	v_mfma_f32_16x16x32_bf16 v[8:11], v[136:139], v[172:175], v[8:11]
	v_mfma_f32_16x16x32_bf16 v[68:71], v[128:131], v[180:183], v[68:71]
	v_mfma_f32_16x16x32_bf16 v[4:7], v[136:139], v[180:183], v[4:7]
	v_mfma_f32_16x16x32_bf16 v[64:67], v[128:131], v[214:217], v[64:67]
	v_mfma_f32_16x16x32_bf16 v[0:3], v[136:139], v[214:217], v[0:3]
	v_mfma_f32_16x16x32_bf16 v[88:91], v[132:135], v[168:171], v[88:91]
	v_mfma_f32_16x16x32_bf16 v[24:27], v[140:143], v[168:171], v[24:27]
	v_mfma_f32_16x16x32_bf16 v[72:75], v[132:135], v[176:179], v[72:75]
	v_mfma_f32_16x16x32_bf16 v[8:11], v[140:143], v[176:179], v[8:11]
	v_mfma_f32_16x16x32_bf16 v[68:71], v[132:135], v[210:213], v[68:71]
	v_mfma_f32_16x16x32_bf16 v[4:7], v[140:143], v[210:213], v[4:7]
	v_mfma_f32_16x16x32_bf16 v[64:67], v[132:135], v[218:221], v[64:67]
	v_mfma_f32_16x16x32_bf16 v[0:3], v[140:143], v[218:221], v[0:3]
	v_mfma_f32_16x16x32_bf16 v[92:95], v[144:147], v[164:167], v[92:95]
	v_mfma_f32_16x16x32_bf16 v[28:31], v[152:155], v[164:167], v[28:31]
	v_mfma_f32_16x16x32_bf16 v[76:79], v[144:147], v[172:175], v[76:79]
	v_mfma_f32_16x16x32_bf16 v[16:19], v[152:155], v[172:175], v[16:19]
	v_mfma_f32_16x16x32_bf16 v[84:87], v[144:147], v[180:183], v[84:87]
	v_mfma_f32_16x16x32_bf16 v[20:23], v[152:155], v[180:183], v[20:23]
	v_mfma_f32_16x16x32_bf16 v[80:83], v[144:147], v[214:217], v[80:83]
	v_mfma_f32_16x16x32_bf16 v[12:15], v[152:155], v[214:217], v[12:15]
	v_mfma_f32_16x16x32_bf16 v[92:95], v[148:151], v[168:171], v[92:95]
	v_mfma_f32_16x16x32_bf16 v[28:31], v[156:159], v[168:171], v[28:31]
	v_mfma_f32_16x16x32_bf16 v[76:79], v[148:151], v[176:179], v[76:79]
	v_mfma_f32_16x16x32_bf16 v[16:19], v[156:159], v[176:179], v[16:19]
	v_mfma_f32_16x16x32_bf16 v[84:87], v[148:151], v[210:213], v[84:87]
	v_mfma_f32_16x16x32_bf16 v[20:23], v[156:159], v[210:213], v[20:23]
	v_mfma_f32_16x16x32_bf16 v[80:83], v[148:151], v[218:221], v[80:83]
	v_mfma_f32_16x16x32_bf16 v[12:15], v[156:159], v[218:221], v[12:15]
	s_barrier
	s_add_i32 s11, s11, 2
	s_addk_i32 s2, 0x100
	s_addk_i32 s3, 0x100
	s_cmp_gt_u32 s11, 13
	s_cbranch_scc1 .Lpeel_done_780
.LBB0_780:
	ds_read_b128 v[128:131], v207
	ds_read_b128 v[132:135], v207 offset:1024
	ds_read_b128 v[136:139], v207 offset:2048
	ds_read_b128 v[140:143], v207 offset:3072
	ds_read_b128 v[144:147], v208
	ds_read_b128 v[148:151], v208 offset:1024
	ds_read_b128 v[152:155], v208 offset:2048
	ds_read_b128 v[156:159], v208 offset:3072
	s_add_i32 s12, s2, 0xffffe080
	s_cmp_eq_u32 s11, 12
	s_cselect_b32 s14, s0, s12
	s_cselect_b32 s13, s1, s3
	s_or_b32 s12, s14, 0x80
	v_add_u32_e32 v184, s2, v206
	ds_read_b128 v[164:167], v209
	ds_read_b128 v[168:171], v209 offset:1024
	ds_read_b128 v[172:175], v209 offset:2048
	ds_read_b128 v[176:179], v209 offset:3072
	ds_read_b128 v[180:183], v209 offset:4096
	ds_read_b128 v[210:213], v209 offset:5120
	ds_read_b128 v[214:217], v209 offset:6144
	ds_read_b128 v[218:221], v209 offset:7168
	s_add_i32 m0, s27, 0xc000
	s_nop 0
	global_load_lds_dwordx4 v184, s[22:23]
	v_add_u32_e32 v184, s2, v205
	s_add_i32 m0, s27, 0xe000
	s_nop 0
	global_load_lds_dwordx4 v184, s[22:23]
	s_waitcnt vmcnt(8)
	s_waitcnt lgkmcnt(0)
	s_barrier
	s_waitcnt lgkmcnt(0)
	v_mfma_f32_16x16x32_bf16 v[120:123], v[128:131], v[164:167], v[120:123]
	v_mfma_f32_16x16x32_bf16 v[56:59], v[136:139], v[164:167], v[56:59]
	v_mfma_f32_16x16x32_bf16 v[112:115], v[128:131], v[172:175], v[112:115]
	v_mfma_f32_16x16x32_bf16 v[48:51], v[136:139], v[172:175], v[48:51]
	v_mfma_f32_16x16x32_bf16 v[104:107], v[128:131], v[180:183], v[104:107]
	v_mfma_f32_16x16x32_bf16 v[40:43], v[136:139], v[180:183], v[40:43]
	v_mfma_f32_16x16x32_bf16 v[96:99], v[128:131], v[214:217], v[96:99]
	v_mfma_f32_16x16x32_bf16 v[32:35], v[136:139], v[214:217], v[32:35]
	v_mfma_f32_16x16x32_bf16 v[120:123], v[132:135], v[168:171], v[120:123]
	v_mfma_f32_16x16x32_bf16 v[56:59], v[140:143], v[168:171], v[56:59]
	v_mfma_f32_16x16x32_bf16 v[112:115], v[132:135], v[176:179], v[112:115]
	v_mfma_f32_16x16x32_bf16 v[48:51], v[140:143], v[176:179], v[48:51]
	v_mfma_f32_16x16x32_bf16 v[104:107], v[132:135], v[210:213], v[104:107]
	v_mfma_f32_16x16x32_bf16 v[40:43], v[140:143], v[210:213], v[40:43]
	v_mfma_f32_16x16x32_bf16 v[96:99], v[132:135], v[218:221], v[96:99]
	v_mfma_f32_16x16x32_bf16 v[32:35], v[140:143], v[218:221], v[32:35]
	v_mfma_f32_16x16x32_bf16 v[124:127], v[144:147], v[164:167], v[124:127]
	v_mfma_f32_16x16x32_bf16 v[60:63], v[152:155], v[164:167], v[60:63]
	v_mfma_f32_16x16x32_bf16 v[116:119], v[144:147], v[172:175], v[116:119]
	v_mfma_f32_16x16x32_bf16 v[52:55], v[152:155], v[172:175], v[52:55]
	v_mfma_f32_16x16x32_bf16 v[108:111], v[144:147], v[180:183], v[108:111]
	v_mfma_f32_16x16x32_bf16 v[44:47], v[152:155], v[180:183], v[44:47]
	v_mfma_f32_16x16x32_bf16 v[100:103], v[144:147], v[214:217], v[100:103]
	v_mfma_f32_16x16x32_bf16 v[36:39], v[152:155], v[214:217], v[36:39]
	v_mfma_f32_16x16x32_bf16 v[124:127], v[148:151], v[168:171], v[124:127]
	v_mfma_f32_16x16x32_bf16 v[60:63], v[156:159], v[168:171], v[60:63]
	v_mfma_f32_16x16x32_bf16 v[116:119], v[148:151], v[176:179], v[116:119]
	v_mfma_f32_16x16x32_bf16 v[52:55], v[156:159], v[176:179], v[52:55]
	v_mfma_f32_16x16x32_bf16 v[108:111], v[148:151], v[210:213], v[108:111]
	v_mfma_f32_16x16x32_bf16 v[44:47], v[156:159], v[210:213], v[44:47]
	v_mfma_f32_16x16x32_bf16 v[100:103], v[148:151], v[218:221], v[100:103]
	v_mfma_f32_16x16x32_bf16 v[36:39], v[156:159], v[218:221], v[36:39]
	s_barrier
	v_add_u32_e32 v184, s13, v192
	s_add_i32 s15, s71, s26
	ds_read_b128 v[164:167], v209 offset:16384
	ds_read_b128 v[168:171], v209 offset:17408
	ds_read_b128 v[172:175], v209 offset:18432
	ds_read_b128 v[176:179], v209 offset:19456
	ds_read_b128 v[180:183], v209 offset:20480
	ds_read_b128 v[210:213], v209 offset:21504
	ds_read_b128 v[214:217], v209 offset:22528
	ds_read_b128 v[218:221], v209 offset:23552
	s_mov_b32 m0, s15
	s_add_i32 s16, s72, s26
	global_load_lds_dwordx4 v184, s[36:37]
	v_add_u32_e32 v184, s13, v194
	s_add_i32 m0, s15, 0x2000
	s_add_i32 s15, s13, 0x40000
	global_load_lds_dwordx4 v184, s[36:37]
	v_add_u32_e32 v184, s15, v192
	s_mov_b32 m0, s16
	s_nop 0
	global_load_lds_dwordx4 v184, s[36:37]
	v_add_u32_e32 v184, s15, v194
	s_add_i32 m0, s16, 0x2000
	s_nop 0
	global_load_lds_dwordx4 v184, s[36:37]
	v_add_u32_e32 v184, s14, v191
	s_mov_b32 m0, s27
	s_nop 0
	global_load_lds_dwordx4 v184, s[22:23]
	v_add_u32_e32 v184, s14, v193
	s_mov_b32 m0, s33
	s_nop 0
	global_load_lds_dwordx4 v184, s[22:23]
	s_waitcnt vmcnt(8)
	s_waitcnt lgkmcnt(0)
	s_barrier
	s_waitcnt lgkmcnt(0)
	v_mfma_f32_16x16x32_bf16 v[88:91], v[128:131], v[164:167], v[88:91]
	v_mfma_f32_16x16x32_bf16 v[24:27], v[136:139], v[164:167], v[24:27]
	v_mfma_f32_16x16x32_bf16 v[72:75], v[128:131], v[172:175], v[72:75]
	v_mfma_f32_16x16x32_bf16 v[8:11], v[136:139], v[172:175], v[8:11]
	v_mfma_f32_16x16x32_bf16 v[68:71], v[128:131], v[180:183], v[68:71]
	v_mfma_f32_16x16x32_bf16 v[4:7], v[136:139], v[180:183], v[4:7]
	v_mfma_f32_16x16x32_bf16 v[64:67], v[128:131], v[214:217], v[64:67]
	v_mfma_f32_16x16x32_bf16 v[0:3], v[136:139], v[214:217], v[0:3]
	v_mfma_f32_16x16x32_bf16 v[88:91], v[132:135], v[168:171], v[88:91]
	v_mfma_f32_16x16x32_bf16 v[24:27], v[140:143], v[168:171], v[24:27]
	v_mfma_f32_16x16x32_bf16 v[72:75], v[132:135], v[176:179], v[72:75]
	v_mfma_f32_16x16x32_bf16 v[8:11], v[140:143], v[176:179], v[8:11]
	v_mfma_f32_16x16x32_bf16 v[68:71], v[132:135], v[210:213], v[68:71]
	v_mfma_f32_16x16x32_bf16 v[4:7], v[140:143], v[210:213], v[4:7]
	v_mfma_f32_16x16x32_bf16 v[64:67], v[132:135], v[218:221], v[64:67]
	v_mfma_f32_16x16x32_bf16 v[0:3], v[140:143], v[218:221], v[0:3]
	v_mfma_f32_16x16x32_bf16 v[92:95], v[144:147], v[164:167], v[92:95]
	v_mfma_f32_16x16x32_bf16 v[28:31], v[152:155], v[164:167], v[28:31]
	v_mfma_f32_16x16x32_bf16 v[76:79], v[144:147], v[172:175], v[76:79]
	v_mfma_f32_16x16x32_bf16 v[16:19], v[152:155], v[172:175], v[16:19]
	v_mfma_f32_16x16x32_bf16 v[84:87], v[144:147], v[180:183], v[84:87]
	v_mfma_f32_16x16x32_bf16 v[20:23], v[152:155], v[180:183], v[20:23]
	v_mfma_f32_16x16x32_bf16 v[80:83], v[144:147], v[214:217], v[80:83]
	v_mfma_f32_16x16x32_bf16 v[12:15], v[152:155], v[214:217], v[12:15]
	v_mfma_f32_16x16x32_bf16 v[92:95], v[148:151], v[168:171], v[92:95]
	v_mfma_f32_16x16x32_bf16 v[28:31], v[156:159], v[168:171], v[28:31]
	v_mfma_f32_16x16x32_bf16 v[76:79], v[148:151], v[176:179], v[76:79]
	v_mfma_f32_16x16x32_bf16 v[16:19], v[156:159], v[176:179], v[16:19]
	v_mfma_f32_16x16x32_bf16 v[84:87], v[148:151], v[210:213], v[84:87]
	v_mfma_f32_16x16x32_bf16 v[20:23], v[156:159], v[210:213], v[20:23]
	v_mfma_f32_16x16x32_bf16 v[80:83], v[148:151], v[218:221], v[80:83]
	v_mfma_f32_16x16x32_bf16 v[12:15], v[156:159], v[218:221], v[12:15]
	s_barrier
; #define PG8_BAR __builtin_amdgcn_s_barrier()
;     ...
;         if constexpr (Epi::MIDHOOK) {
;             for (int t = 0; t < 4; t += 2) PG8_ITER(t);
;             E.mid(acc, cur, wr, wc, fr, fq);
;             for (int t = 4; t < nt; t += 2) PG8_ITER(t);
;         } else {
;             for (int t = 0; t < nt; t += 2) PG8_ITER(t);
;         }
;     ...
;         if constexpr (ALIGN_EPI) { if (wr == 0) PG8_BAR; }
	s_add_i32 s15, 0, 0x18000
	s_add_i32 s16, 0, 0x1c000
	v_add_u32_e32 v140, s15, v195
	v_add_u32_e32 v156, s16, v195
	ds_read_b128 v[128:131], v140
	ds_read_b128 v[132:135], v140 offset:1024
	ds_read_b128 v[136:139], v140 offset:2048
	ds_read_b128 v[140:143], v140 offset:3072
	ds_read_b128 v[144:147], v156
	ds_read_b128 v[148:151], v156 offset:1024
	ds_read_b128 v[152:155], v156 offset:2048
	ds_read_b128 v[156:159], v156 offset:3072
	s_addk_i32 s14, 0x2000
	v_add_u32_e32 v184, s14, v191
	s_mov_b32 m0, s34
	ds_read_b128 v[164:167], v209 offset:32768
	ds_read_b128 v[168:171], v209 offset:33792
	ds_read_b128 v[172:175], v209 offset:34816
	ds_read_b128 v[176:179], v209 offset:35840
	ds_read_b128 v[180:183], v209 offset:36864
	ds_read_b128 v[210:213], v209 offset:37888
	ds_read_b128 v[214:217], v209 offset:38912
	ds_read_b128 v[218:221], v209 offset:39936
	s_nop 0
	global_load_lds_dwordx4 v184, s[22:23]
	v_add_u32_e32 v184, s14, v193
	s_mov_b32 m0, s35
	s_nop 0
	global_load_lds_dwordx4 v184, s[22:23]
	s_waitcnt vmcnt(8)
	s_waitcnt lgkmcnt(0)
	s_barrier
	s_waitcnt lgkmcnt(0)
	v_mfma_f32_16x16x32_bf16 v[120:123], v[128:131], v[164:167], v[120:123]
	v_mfma_f32_16x16x32_bf16 v[56:59], v[136:139], v[164:167], v[56:59]
	v_mfma_f32_16x16x32_bf16 v[112:115], v[128:131], v[172:175], v[112:115]
	v_mfma_f32_16x16x32_bf16 v[48:51], v[136:139], v[172:175], v[48:51]
	v_mfma_f32_16x16x32_bf16 v[104:107], v[128:131], v[180:183], v[104:107]
	v_mfma_f32_16x16x32_bf16 v[40:43], v[136:139], v[180:183], v[40:43]
	v_mfma_f32_16x16x32_bf16 v[96:99], v[128:131], v[214:217], v[96:99]
	v_mfma_f32_16x16x32_bf16 v[32:35], v[136:139], v[214:217], v[32:35]
	v_mfma_f32_16x16x32_bf16 v[120:123], v[132:135], v[168:171], v[120:123]
	v_mfma_f32_16x16x32_bf16 v[56:59], v[140:143], v[168:171], v[56:59]
	v_mfma_f32_16x16x32_bf16 v[112:115], v[132:135], v[176:179], v[112:115]
	v_mfma_f32_16x16x32_bf16 v[48:51], v[140:143], v[176:179], v[48:51]
	v_mfma_f32_16x16x32_bf16 v[104:107], v[132:135], v[210:213], v[104:107]
	v_mfma_f32_16x16x32_bf16 v[40:43], v[140:143], v[210:213], v[40:43]
	v_mfma_f32_16x16x32_bf16 v[96:99], v[132:135], v[218:221], v[96:99]
	v_mfma_f32_16x16x32_bf16 v[32:35], v[140:143], v[218:221], v[32:35]
	v_mfma_f32_16x16x32_bf16 v[124:127], v[144:147], v[164:167], v[124:127]
	v_mfma_f32_16x16x32_bf16 v[60:63], v[152:155], v[164:167], v[60:63]
	v_mfma_f32_16x16x32_bf16 v[116:119], v[144:147], v[172:175], v[116:119]
	v_mfma_f32_16x16x32_bf16 v[52:55], v[152:155], v[172:175], v[52:55]
	v_mfma_f32_16x16x32_bf16 v[108:111], v[144:147], v[180:183], v[108:111]
	v_mfma_f32_16x16x32_bf16 v[44:47], v[152:155], v[180:183], v[44:47]
	v_mfma_f32_16x16x32_bf16 v[100:103], v[144:147], v[214:217], v[100:103]
	v_mfma_f32_16x16x32_bf16 v[36:39], v[152:155], v[214:217], v[36:39]
	v_mfma_f32_16x16x32_bf16 v[124:127], v[148:151], v[168:171], v[124:127]
	v_mfma_f32_16x16x32_bf16 v[60:63], v[156:159], v[168:171], v[60:63]
	v_mfma_f32_16x16x32_bf16 v[116:119], v[148:151], v[176:179], v[116:119]
	v_mfma_f32_16x16x32_bf16 v[52:55], v[156:159], v[176:179], v[52:55]
	v_mfma_f32_16x16x32_bf16 v[108:111], v[148:151], v[210:213], v[108:111]
	v_mfma_f32_16x16x32_bf16 v[44:47], v[156:159], v[210:213], v[44:47]
	v_mfma_f32_16x16x32_bf16 v[100:103], v[148:151], v[218:221], v[100:103]
	v_mfma_f32_16x16x32_bf16 v[36:39], v[156:159], v[218:221], v[36:39]
	s_barrier
	s_or_b32 s14, s13, 0x80
	v_add_u32_e32 v184, s14, v192
	s_add_i32 s15, s15, s26
	ds_read_b128 v[164:167], v209 offset:49152
	ds_read_b128 v[168:171], v209 offset:50176
	ds_read_b128 v[172:175], v209 offset:51200
	ds_read_b128 v[176:179], v209 offset:52224
	ds_read_b128 v[180:183], v209 offset:53248
	ds_read_b128 v[210:213], v209 offset:54272
	ds_read_b128 v[214:217], v209 offset:55296
	ds_read_b128 v[218:221], v209 offset:56320
	s_mov_b32 m0, s15
	s_add_i32 s13, s13, 0x40080
	global_load_lds_dwordx4 v184, s[36:37]
	v_add_u32_e32 v184, s14, v194
	s_add_i32 m0, s15, 0x2000
	s_add_i32 s14, s16, s26
	global_load_lds_dwordx4 v184, s[36:37]
	v_add_u32_e32 v184, s13, v192
	s_mov_b32 m0, s14
	s_nop 0
	global_load_lds_dwordx4 v184, s[36:37]
	v_add_u32_e32 v184, s13, v194
	s_add_i32 m0, s14, 0x2000
	s_nop 0
	global_load_lds_dwordx4 v184, s[36:37]
	v_add_u32_e32 v184, s12, v191
	s_mov_b32 m0, s61
	s_nop 0
	global_load_lds_dwordx4 v184, s[22:23]
	v_add_u32_e32 v184, s12, v193
	s_mov_b32 m0, s63
	s_nop 0
	global_load_lds_dwordx4 v184, s[22:23]
	s_waitcnt vmcnt(8)
	s_waitcnt lgkmcnt(0)
	s_barrier
	s_waitcnt lgkmcnt(0)
	v_mfma_f32_16x16x32_bf16 v[88:91], v[128:131], v[164:167], v[88:91]
	v_mfma_f32_16x16x32_bf16 v[24:27], v[136:139], v[164:167], v[24:27]
	v_mfma_f32_16x16x32_bf16 v[72:75], v[128:131], v[172:175], v[72:75]
	v_mfma_f32_16x16x32_bf16 v[8:11], v[136:139], v[172:175], v[8:11]
	v_mfma_f32_16x16x32_bf16 v[68:71], v[128:131], v[180:183], v[68:71]
	v_mfma_f32_16x16x32_bf16 v[4:7], v[136:139], v[180:183], v[4:7]
	v_mfma_f32_16x16x32_bf16 v[64:67], v[128:131], v[214:217], v[64:67]
	v_mfma_f32_16x16x32_bf16 v[0:3], v[136:139], v[214:217], v[0:3]
	v_mfma_f32_16x16x32_bf16 v[88:91], v[132:135], v[168:171], v[88:91]
	v_mfma_f32_16x16x32_bf16 v[24:27], v[140:143], v[168:171], v[24:27]
	v_mfma_f32_16x16x32_bf16 v[72:75], v[132:135], v[176:179], v[72:75]
	v_mfma_f32_16x16x32_bf16 v[8:11], v[140:143], v[176:179], v[8:11]
	v_mfma_f32_16x16x32_bf16 v[68:71], v[132:135], v[210:213], v[68:71]
	v_mfma_f32_16x16x32_bf16 v[4:7], v[140:143], v[210:213], v[4:7]
	v_mfma_f32_16x16x32_bf16 v[64:67], v[132:135], v[218:221], v[64:67]
	v_mfma_f32_16x16x32_bf16 v[0:3], v[140:143], v[218:221], v[0:3]
	v_mfma_f32_16x16x32_bf16 v[92:95], v[144:147], v[164:167], v[92:95]
	v_mfma_f32_16x16x32_bf16 v[28:31], v[152:155], v[164:167], v[28:31]
	v_mfma_f32_16x16x32_bf16 v[76:79], v[144:147], v[172:175], v[76:79]
	v_mfma_f32_16x16x32_bf16 v[16:19], v[152:155], v[172:175], v[16:19]
	v_mfma_f32_16x16x32_bf16 v[84:87], v[144:147], v[180:183], v[84:87]
	v_mfma_f32_16x16x32_bf16 v[20:23], v[152:155], v[180:183], v[20:23]
	v_mfma_f32_16x16x32_bf16 v[80:83], v[144:147], v[214:217], v[80:83]
	v_mfma_f32_16x16x32_bf16 v[12:15], v[152:155], v[214:217], v[12:15]
	v_mfma_f32_16x16x32_bf16 v[92:95], v[148:151], v[168:171], v[92:95]
	v_mfma_f32_16x16x32_bf16 v[28:31], v[156:159], v[168:171], v[28:31]
	v_mfma_f32_16x16x32_bf16 v[76:79], v[148:151], v[176:179], v[76:79]
	v_mfma_f32_16x16x32_bf16 v[16:19], v[156:159], v[176:179], v[16:19]
	v_mfma_f32_16x16x32_bf16 v[84:87], v[148:151], v[210:213], v[84:87]
	v_mfma_f32_16x16x32_bf16 v[20:23], v[156:159], v[210:213], v[20:23]
	v_mfma_f32_16x16x32_bf16 v[80:83], v[148:151], v[218:221], v[80:83]
	v_mfma_f32_16x16x32_bf16 v[12:15], v[156:159], v[218:221], v[12:15]
	s_barrier
	s_add_i32 s11, s11, 2
	s_addk_i32 s2, 0x100
	s_addk_i32 s3, 0x100
	s_cmp_gt_u32 s11, 13
	s_cbranch_scc0 .LBB0_780
.Lpeel_done_780:
	s_and_b64 vcc, exec, s[42:43]
	s_cbranch_vccz .LBB0_783
	s_barrier
